# RWKV-7 scan: features widened to f32 in LDS by the idle waves, packed f32 step math (same f32 ops), staging moved off the recurrence waves
# speedup vs baseline: 1.2060x; 1.0210x over previous
; #define TIDX tid_fn()
; #define RW_LOAD(slot, step) do { const size_t ro_ = (size_t)row_of(step) * RWW; \
;       s_ok[slot] = *(const h16x8*)((p_rec + ro_ * 3) + urec); s_b[slot] = *(const h16x4*)((p_rec + ro_ * 3) + urec + 8); \
;       s_kr[slot] = *(const h16x8*)((p_sh + ro_ * 2) + ush); s_v[slot] = (p_v + ro_)[uvoff]; } while (0)
; template <int VAR>
; __device__ __forceinline__ void ph_rw_scan(const Params& P) {
;   RwFeat F = rw_feat(P);
;   h16* yout = (h16*)(P.ws + O_PRW);
;     ...
;   const int tid = TIDX, wave = tid / 64, lane = tid % 64;
;     ...
;   const int tid = TIDX, wave = __builtin_amdgcn_readfirstlane(tid / 64), lane = tid % 64;
;     ...
;   const int rl = lane / 16, q = lane % 16;
;   constexpr int NWU = 2 * BATCH * RW_H * 16;
;   for (int wu = blockIdx.x * 4 + wave; wave < 4 && wu < NWU; wu += gridDim.x * 4) {
;     const int rg = wu % 16, hh = (wu / 16) % RW_H, b = (wu / (16 * RW_H)) % BATCH, dir = wu / (16 * RW_H * BATCH);
;     const int vrow = rg * 4 + rl;
;     ...
;     const unsigned g_ = (unsigned)(hh * 16 + q);
;     const unsigned uvoff = (unsigned)(hh * 64 + vrow), urec = g_ * 12u, ush = g_ * 8u;
;     h16x8 s_ok[RW_U], s_kr[RW_U]; h16x4 s_b[RW_U]; h16 s_v[RW_U];
;     auto row_of = [&](int step) -> int {
;       if (step < CTX_LEN) return NL + b * CTX_LEN + (dir == 0 ? step : CTX_LEN - 1 - step);
;       const int s = step - CTX_LEN; return b * SEQ + (dir == 0 ? s : SEQ - 1 - s);
;     };
;     ...
; #pragma unroll
;     for (int uu = 0; uu < RW_U; ++uu) RW_LOAD(uu, uu);
;     float S[4] = {0.f, 0.f, 0.f, 0.f};
;     for (int t0 = 0; t0 < RW_NS; t0 += RW_U) {
.LBB0_3117:
	s_or_b64 exec, exec, s[6:7]
	s_mov_b64 s[4:5], s[96:97]
	s_waitcnt lgkmcnt(0)
	v_mov_b32_e32 v1, v0
	s_barrier
	v_readfirstlane_b32 s1, v0
	s_lshr_b32 s1, s1, 6
	s_lshl_b32 s0, s2, 2
	s_cmp_gt_u32 s0, 0x3ff
	s_cbranch_scc1 .LBB0_3154
	s_load_dwordx2 s[4:5], s[96:97], 0x178
	v_and_b32_e32 v1, 63, v0
	v_and_b32_e32 v2, 15, v1
	v_lshrrev_b32_e32 v3, 4, v1
	v_lshlrev_b32_e32 v8, 4, v2
	s_and_b32 s30, s1, 3
	s_lshl_b32 s30, s30, 10
	v_lshl_add_u32 v12, v1, 4, s30
	s_mov_b32 s20, 0x22222222
	s_mov_b32 s21, 0x22222222
	s_mov_b32 s22, 0x44444444
	s_mov_b32 s23, 0x44444444
	s_mov_b32 s24, 0x88888888
	s_mov_b32 s25, 0x88888888
	s_waitcnt lgkmcnt(0)
.Lscan_unit:
	s_lshr_b32 s31, s0, 2
	s_and_b32 s26, s31, 7
	s_lshr_b32 s31, s31, 3
	s_and_b32 s27, s31, 3
	s_lshr_b32 s31, s31, 2
	s_lshl_b32 s26, s26, 3
	s_add_u32 s31, s31, s26
	s_lshl_b32 s26, s27, 2
	s_and_b32 s30, s1, 3
	s_add_u32 s26, s26, s30
	s_and_b32 s27, s31, 15
	s_bfe_u32 s28, s31, 0x10004
	s_lshr_b32 s29, s31, 5
	s_lshl_b32 s30, s27, 4
	v_add_u32_e32 v4, s30, v2
	v_mul_u32_u24_e32 v5, 24, v4
	v_lshlrev_b32_e32 v6, 4, v4
	s_lshl_b32 s30, s27, 6
	s_lshl_b32 s31, s26, 2
	s_add_u32 s30, s30, s31
	v_add_u32_e32 v7, s30, v3
	v_lshlrev_b32_e32 v7, 1, v7
	s_cmp_gt_u32 s1, 3
	s_cbranch_scc1 .Lscan_follow
	s_cmp_lg_u32 s29, 0
	s_cbranch_scc1 .Lscan_dir1
	v_lshlrev_b32_e32 v44, 11, v2
	v_add_u32_e32 v44, v44, v7
	s_lshl_b32 s30, s28, 8
	s_add_u32 s30, s30, 0x8000
	s_lshl_b32 s31, s28, 14
	s_mul_i32 s3, s30, 0x800
	s_add_u32 s10, s4, s3
	s_addc_u32 s11, s5, 0
	s_add_u32 s10, s10, 0x3bc14000
	s_addc_u32 s11, s11, 0
	s_mul_i32 s3, s31, 0x800
	s_add_u32 s18, s4, s3
	s_addc_u32 s19, s5, 0
	s_add_u32 s18, s18, 0x3bc14000
	s_addc_u32 s19, s19, 0
	s_mul_i32 s3, s31, 0x800
	s_add_u32 s12, s4, s3
	s_addc_u32 s13, s5, 0
	s_add_u32 s12, s12, 0x160cc000
	s_addc_u32 s13, s13, 0
	v_mov_b32_e32 v10, 0
	v_mov_b32_e32 v11, 0
	v_mov_b32_e32 v12, 0
	v_mov_b32_e32 v13, 0
	global_load_ushort v42, v44, s[10:11]
	s_mov_b32 s26, 0
	s_mov_b32 s27, 20480
	v_add_u32_e32 v46, s26, v8
	v_add_u32_e32 v47, s27, v8
	s_waitcnt vmcnt(0) lgkmcnt(0)
	v_cvt_f32_f16_e32 v42, v42
	s_barrier
	ds_read_b128 v[48:51], v46
	ds_read_b128 v[60:63], v46 offset:12288
	ds_read_b128 v[52:55], v46 offset:4096
	ds_read_b128 v[56:59], v46 offset:8192
	ds_read_b128 v[64:67], v46 offset:16384
	ds_read_b128 v[68:71], v46 offset:256
	ds_read_b128 v[80:83], v46 offset:12544
	ds_read_b128 v[72:75], v46 offset:4352
	ds_read_b128 v[76:79], v46 offset:8448
	ds_read_b128 v[84:87], v46 offset:16640
	ds_read_b128 v[88:91], v46 offset:512
	ds_read_b128 v[100:103], v46 offset:12800
	ds_read_b128 v[92:95], v46 offset:4608
	ds_read_b128 v[96:99], v46 offset:8704
	ds_read_b128 v[104:107], v46 offset:16896
	s_mov_b32 s3, 0
	s_waitcnt lgkmcnt(10)
.Lscan_loop_d0:
	v_mov_b32_dpp v20, v42 row_newbcast:0 row_mask:0xf bank_mask:0xf
	v_pk_mul_f32 v[22:23], v[10:11], v[60:61]
	v_pk_fma_f32 v[22:23], v[12:13], v[62:63], v[22:23]
	v_pk_fma_f32 v[14:15], v[10:11], v[48:49], v[10:11]
	v_add_f32_e32 v18, v22, v23
	v_pk_fma_f32 v[16:17], v[12:13], v[50:51], v[12:13]
	v_pk_fma_f32 v[14:15], v[20:21], v[52:53], v[14:15] op_sel_hi:[0,1,1]
	v_add_f32_dpp v18, v18, v18 quad_perm:[1,0,3,2] row_mask:0xf bank_mask:0xf bound_ctrl:1
	v_pk_fma_f32 v[16:17], v[20:21], v[54:55], v[16:17] op_sel_hi:[0,1,1]
	v_pk_mul_f32 v[24:25], v[10:11], v[124:125]
	v_add_f32_dpp v18, v18, v18 quad_perm:[2,3,0,1] row_mask:0xf bank_mask:0xf bound_ctrl:1
	v_pk_fma_f32 v[24:25], v[12:13], v[126:127], v[24:25]
	s_waitcnt lgkmcnt(5)
	ds_read_b128 v[108:111], v46 offset:768
	v_add_f32_dpp v18, v18, v18 row_ror:4 row_mask:0xf bank_mask:0xf bound_ctrl:1
	ds_read_b128 v[120:123], v46 offset:13056
	v_add_f32_e32 v41, v24, v25
	ds_read_b128 v[112:115], v46 offset:4864
	v_add_f32_dpp v18, v18, v18 row_ror:8 row_mask:0xf bank_mask:0xf bound_ctrl:1
	ds_read_b128 v[116:119], v46 offset:8960
	ds_read_b128 v[124:127], v46 offset:17152
	v_pk_fma_f32 v[10:11], v[18:19], v[56:57], v[14:15] op_sel_hi:[0,1,1]
	v_pk_fma_f32 v[12:13], v[18:19], v[58:59], v[16:17] op_sel_hi:[0,1,1]
	s_cmp_eq_u32 s3, 15
	s_cbranch_scc1 .Lscan_vsw_d0
	s_add_u32 s10, s10, 0x8000
	s_addc_u32 s11, s11, 0
	s_branch .Lscan_vdone_d0

; __device__ __forceinline__ float row_sum16(float v) { v += __shfl_xor(v, 1); v += __shfl_xor(v, 2); v += __shfl_xor(v, 4); v += __shfl_xor(v, 8); return v; }
; __device__ __forceinline__ float row_sum16(float v) { v += dppf<0xB1>(v); v += dppf<0x4E>(v); v += dppf<0x124>(v); v += dppf<0x128>(v); return v; }
; #define RW_LOAD(slot, step) do { const size_t ro_ = (size_t)row_of(step) * RWW; \
;       s_ok[slot] = *(const h16x8*)((p_rec + ro_ * 3) + urec); s_b[slot] = *(const h16x4*)((p_rec + ro_ * 3) + urec + 8); \
;       s_kr[slot] = *(const h16x8*)((p_sh + ro_ * 2) + ush); s_v[slot] = (p_v + ro_)[uvoff]; } while (0)
; template <int VAR>
; __device__ __forceinline__ void ph_rw_scan(const Params& P) {
;     ...
; #pragma unroll
;       for (int uu = 0; uu < RW_U; ++uu) {
;         const float vv = (float)s_v[uu];
;         const u32x4 p_ok = __builtin_bit_cast(u32x4, s_ok[uu]), p_kr = __builtin_bit_cast(u32x4, s_kr[uu]);
;         const u32x2 p_bb = __builtin_bit_cast(u32x2, s_b[uu]);
;         const unsigned om0 = p_ok[0], om1 = p_ok[1], kd0 = p_ok[2], kd1 = p_ok[3];
;         const unsigned kk0 = p_kr[0], kk1 = p_kr[1], r0_ = p_kr[2], r1_ = p_kr[3];
;         const unsigned b0_ = p_bb[0], b1_ = p_bb[1];
;         float sa = fmix_lo(S[0], kk0, 0.f); sa = fmix_hi(S[1], kk0, sa);
;         float sb = fmix_lo(S[2], kk1, 0.f); sb = fmix_hi(S[3], kk1, sb);
;         sa = row_sum16(sa + sb);
;         S[0] = fmix_lo(S[0], om0, S[0]); S[1] = fmix_hi(S[1], om0, S[1]); S[2] = fmix_lo(S[2], om1, S[2]); S[3] = fmix_hi(S[3], om1, S[3]);
;         S[0] = fmix_lo(sa, b0_, S[0]); S[1] = fmix_hi(sa, b0_, S[1]); S[2] = fmix_lo(sa, b1_, S[2]); S[3] = fmix_hi(sa, b1_, S[3]);
;         S[0] = fmix_lo(vv, kd0, S[0]); S[1] = fmix_hi(vv, kd0, S[1]); S[2] = fmix_lo(vv, kd1, S[2]); S[3] = fmix_hi(vv, kd1, S[3]);
;         float y = fmix_lo(S[0], r0_, 0.f); y = fmix_hi(S[1], r0_, y);
;         float y2 = fmix_lo(S[2], r1_, 0.f); y2 = fmix_hi(S[3], r1_, y2);
;         y += y2;
;         if (VAR == 0 && islat) {
;           y = row_sum16(y);
;           if (q == 0) yout[((size_t)dir * NL + row_of(t0 + uu)) * RWW + hh * 64 + vrow] = (h16)y;
;         }
;         if (VAR != 0) asm volatile("" :: "v"(y));
;         const int nstep = t0 + uu + RW_U < RW_NS ? t0 + uu + RW_U : RW_NS - 1;
;         if (VAR != 2) RW_LOAD(uu, nstep);
.Lscan_vdone_d0:
	global_load_ushort v43, v44, s[10:11]
	s_cmp_lt_u32 s3, 17
	s_cbranch_scc1 .Lscan_noy_d0
	v_add_f32_dpp v26, v26, v26 row_ror:8 row_mask:0xf bank_mask:0xf bound_ctrl:1
	v_add_f32_dpp v27, v27, v27 row_ror:8 row_mask:0xf bank_mask:0xf bound_ctrl:1
	v_add_f32_dpp v28, v28, v28 row_ror:8 row_mask:0xf bank_mask:0xf bound_ctrl:1
	v_add_f32_dpp v29, v29, v29 row_ror:8 row_mask:0xf bank_mask:0xf bound_ctrl:1
	v_add_f32_dpp v30, v30, v30 row_ror:8 row_mask:0xf bank_mask:0xf bound_ctrl:1
	v_add_f32_dpp v31, v31, v31 row_ror:8 row_mask:0xf bank_mask:0xf bound_ctrl:1
	v_add_f32_dpp v32, v32, v32 row_ror:8 row_mask:0xf bank_mask:0xf bound_ctrl:1
	v_add_f32_dpp v33, v33, v33 row_ror:8 row_mask:0xf bank_mask:0xf bound_ctrl:1
	v_add_f32_dpp v26, v34, v34 row_ror:8 row_mask:0xf bank_mask:0xc bound_ctrl:1
	v_add_f32_dpp v27, v35, v35 row_ror:8 row_mask:0xf bank_mask:0xc bound_ctrl:1
	v_add_f32_dpp v28, v36, v36 row_ror:8 row_mask:0xf bank_mask:0xc bound_ctrl:1
	v_add_f32_dpp v29, v37, v37 row_ror:8 row_mask:0xf bank_mask:0xc bound_ctrl:1
	v_add_f32_dpp v30, v38, v38 row_ror:8 row_mask:0xf bank_mask:0xc bound_ctrl:1
	v_add_f32_dpp v31, v39, v39 row_ror:8 row_mask:0xf bank_mask:0xc bound_ctrl:1
	v_add_f32_dpp v32, v40, v40 row_ror:8 row_mask:0xf bank_mask:0xc bound_ctrl:1
	v_add_f32_dpp v33, v41, v41 row_ror:8 row_mask:0xf bank_mask:0xc bound_ctrl:1
	v_add_f32_dpp v26, v26, v26 row_half_mirror row_mask:0xf bank_mask:0xf bound_ctrl:1
	v_add_f32_dpp v27, v27, v27 row_half_mirror row_mask:0xf bank_mask:0xf bound_ctrl:1
	v_add_f32_dpp v28, v28, v28 row_half_mirror row_mask:0xf bank_mask:0xf bound_ctrl:1
	v_add_f32_dpp v29, v29, v29 row_half_mirror row_mask:0xf bank_mask:0xf bound_ctrl:1
	v_add_f32_dpp v26, v30, v30 row_half_mirror row_mask:0xf bank_mask:0xa bound_ctrl:1
	v_add_f32_dpp v27, v31, v31 row_half_mirror row_mask:0xf bank_mask:0xa bound_ctrl:1
	v_add_f32_dpp v28, v32, v32 row_half_mirror row_mask:0xf bank_mask:0xa bound_ctrl:1
	v_add_f32_dpp v29, v33, v33 row_half_mirror row_mask:0xf bank_mask:0xa bound_ctrl:1
	v_add_f32_dpp v26, v26, v26 quad_perm:[1,0,3,2] row_mask:0xf bank_mask:0xf bound_ctrl:1
	v_add_f32_dpp v27, v27, v27 quad_perm:[1,0,3,2] row_mask:0xf bank_mask:0xf bound_ctrl:1
	v_add_f32_dpp v28, v28, v28 quad_perm:[1,0,3,2] row_mask:0xf bank_mask:0xf bound_ctrl:1
	v_add_f32_dpp v29, v29, v29 quad_perm:[1,0,3,2] row_mask:0xf bank_mask:0xf bound_ctrl:1
	v_add_f32_dpp v26, v26, v26 quad_perm:[2,3,0,1] row_mask:0xf bank_mask:0xf bound_ctrl:1
	v_add_f32_dpp v27, v27, v27 quad_perm:[2,3,0,1] row_mask:0xf bank_mask:0xf bound_ctrl:1
	v_add_f32_dpp v28, v28, v28 quad_perm:[2,3,0,1] row_mask:0xf bank_mask:0xf bound_ctrl:1
	v_add_f32_dpp v29, v29, v29 quad_perm:[2,3,0,1] row_mask:0xf bank_mask:0xf bound_ctrl:1
	v_cndmask_b32_e64 v26, v26, v27, s[20:21]
	v_cndmask_b32_e64 v26, v26, v28, s[22:23]
	v_cndmask_b32_e64 v26, v26, v29, s[24:25]
	v_cvt_f16_f32_e32 v45, v26
	global_store_short v44, v45, s[12:13]
	s_add_u32 s12, s12, 0x8000
	s_addc_u32 s13, s13, 0
.Lscan_noy_d0:
	v_mov_b32_dpp v20, v42 row_newbcast:1 row_mask:0xf bank_mask:0xf
	v_pk_mul_f32 v[22:23], v[10:11], v[80:81]
	v_pk_fma_f32 v[22:23], v[12:13], v[82:83], v[22:23]
	v_pk_fma_f32 v[14:15], v[10:11], v[68:69], v[10:11]
	v_add_f32_e32 v18, v22, v23
	v_pk_fma_f32 v[16:17], v[12:13], v[70:71], v[12:13]
	v_pk_fma_f32 v[14:15], v[20:21], v[72:73], v[14:15] op_sel_hi:[0,1,1]
	v_add_f32_dpp v18, v18, v18 quad_perm:[1,0,3,2] row_mask:0xf bank_mask:0xf bound_ctrl:1
	v_pk_fma_f32 v[16:17], v[20:21], v[74:75], v[16:17] op_sel_hi:[0,1,1]
	v_pk_mul_f32 v[24:25], v[10:11], v[64:65]
	v_add_f32_dpp v18, v18, v18 quad_perm:[2,3,0,1] row_mask:0xf bank_mask:0xf bound_ctrl:1
	v_pk_fma_f32 v[24:25], v[12:13], v[66:67], v[24:25]
	s_waitcnt lgkmcnt(5)
	ds_read_b128 v[48:51], v46 offset:1024
	v_add_f32_dpp v18, v18, v18 row_ror:4 row_mask:0xf bank_mask:0xf bound_ctrl:1
	ds_read_b128 v[60:63], v46 offset:13312
	v_add_f32_e32 v26, v24, v25
	ds_read_b128 v[52:55], v46 offset:5120
	v_add_f32_dpp v18, v18, v18 row_ror:8 row_mask:0xf bank_mask:0xf bound_ctrl:1
	ds_read_b128 v[56:59], v46 offset:9216
	ds_read_b128 v[64:67], v46 offset:17408
	v_pk_fma_f32 v[10:11], v[18:19], v[76:77], v[14:15] op_sel_hi:[0,1,1]
	v_pk_fma_f32 v[12:13], v[18:19], v[78:79], v[16:17] op_sel_hi:[0,1,1]
	v_mov_b32_dpp v20, v42 row_newbcast:2 row_mask:0xf bank_mask:0xf
	v_pk_mul_f32 v[22:23], v[10:11], v[100:101]
	v_pk_fma_f32 v[22:23], v[12:13], v[102:103], v[22:23]
	v_pk_fma_f32 v[14:15], v[10:11], v[88:89], v[10:11]
	v_add_f32_e32 v18, v22, v23
	v_pk_fma_f32 v[16:17], v[12:13], v[90:91], v[12:13]
	v_pk_fma_f32 v[14:15], v[20:21], v[92:93], v[14:15] op_sel_hi:[0,1,1]
	v_add_f32_dpp v18, v18, v18 quad_perm:[1,0,3,2] row_mask:0xf bank_mask:0xf bound_ctrl:1
	v_pk_fma_f32 v[16:17], v[20:21], v[94:95], v[16:17] op_sel_hi:[0,1,1]
	v_pk_mul_f32 v[24:25], v[10:11], v[84:85]
	v_add_f32_dpp v18, v18, v18 quad_perm:[2,3,0,1] row_mask:0xf bank_mask:0xf bound_ctrl:1
	v_pk_fma_f32 v[24:25], v[12:13], v[86:87], v[24:25]
	s_waitcnt lgkmcnt(5)
; __device__ __forceinline__ float row_sum16(float v) { v += __shfl_xor(v, 1); v += __shfl_xor(v, 2); v += __shfl_xor(v, 4); v += __shfl_xor(v, 8); return v; }
; __device__ __forceinline__ float row_sum16(float v) { v += dppf<0xB1>(v); v += dppf<0x4E>(v); v += dppf<0x124>(v); v += dppf<0x128>(v); return v; }
; #define RW_LOAD(slot, step) do { const size_t ro_ = (size_t)row_of(step) * RWW; \
;       s_ok[slot] = *(const h16x8*)((p_rec + ro_ * 3) + urec); s_b[slot] = *(const h16x4*)((p_rec + ro_ * 3) + urec + 8); \
;       s_kr[slot] = *(const h16x8*)((p_sh + ro_ * 2) + ush); s_v[slot] = (p_v + ro_)[uvoff]; } while (0)
; template <int VAR>
; __device__ __forceinline__ void ph_rw_scan(const Params& P) {
;     ...
; #pragma unroll
;       for (int uu = 0; uu < RW_U; ++uu) {
;         const float vv = (float)s_v[uu];
;         const u32x4 p_ok = __builtin_bit_cast(u32x4, s_ok[uu]), p_kr = __builtin_bit_cast(u32x4, s_kr[uu]);
;         const u32x2 p_bb = __builtin_bit_cast(u32x2, s_b[uu]);
;         const unsigned om0 = p_ok[0], om1 = p_ok[1], kd0 = p_ok[2], kd1 = p_ok[3];
;         const unsigned kk0 = p_kr[0], kk1 = p_kr[1], r0_ = p_kr[2], r1_ = p_kr[3];
;         const unsigned b0_ = p_bb[0], b1_ = p_bb[1];
;         float sa = fmix_lo(S[0], kk0, 0.f); sa = fmix_hi(S[1], kk0, sa);
;         float sb = fmix_lo(S[2], kk1, 0.f); sb = fmix_hi(S[3], kk1, sb);
;         sa = row_sum16(sa + sb);
;         S[0] = fmix_lo(S[0], om0, S[0]); S[1] = fmix_hi(S[1], om0, S[1]); S[2] = fmix_lo(S[2], om1, S[2]); S[3] = fmix_hi(S[3], om1, S[3]);
;         S[0] = fmix_lo(sa, b0_, S[0]); S[1] = fmix_hi(sa, b0_, S[1]); S[2] = fmix_lo(sa, b1_, S[2]); S[3] = fmix_hi(sa, b1_, S[3]);
;         S[0] = fmix_lo(vv, kd0, S[0]); S[1] = fmix_hi(vv, kd0, S[1]); S[2] = fmix_lo(vv, kd1, S[2]); S[3] = fmix_hi(vv, kd1, S[3]);
;         float y = fmix_lo(S[0], r0_, 0.f); y = fmix_hi(S[1], r0_, y);
;         float y2 = fmix_lo(S[2], r1_, 0.f); y2 = fmix_hi(S[3], r1_, y2);
;         y += y2;
;         if (VAR == 0 && islat) {
;           y = row_sum16(y);
;           if (q == 0) yout[((size_t)dir * NL + row_of(t0 + uu)) * RWW + hh * 64 + vrow] = (h16)y;
;         }
;         if (VAR != 0) asm volatile("" :: "v"(y));
;         const int nstep = t0 + uu + RW_U < RW_NS ? t0 + uu + RW_U : RW_NS - 1;
;         if (VAR != 2) RW_LOAD(uu, nstep);
	ds_read_b128 v[68:71], v46 offset:1280
	v_add_f32_dpp v18, v18, v18 row_ror:4 row_mask:0xf bank_mask:0xf bound_ctrl:1
	ds_read_b128 v[80:83], v46 offset:13568
	v_add_f32_e32 v27, v24, v25
	ds_read_b128 v[72:75], v46 offset:5376
	v_add_f32_dpp v18, v18, v18 row_ror:8 row_mask:0xf bank_mask:0xf bound_ctrl:1
	ds_read_b128 v[76:79], v46 offset:9472
	ds_read_b128 v[84:87], v46 offset:17664
	v_pk_fma_f32 v[10:11], v[18:19], v[96:97], v[14:15] op_sel_hi:[0,1,1]
	v_pk_fma_f32 v[12:13], v[18:19], v[98:99], v[16:17] op_sel_hi:[0,1,1]
	v_mov_b32_dpp v20, v42 row_newbcast:3 row_mask:0xf bank_mask:0xf
	v_pk_mul_f32 v[22:23], v[10:11], v[120:121]
	v_pk_fma_f32 v[22:23], v[12:13], v[122:123], v[22:23]
	v_pk_fma_f32 v[14:15], v[10:11], v[108:109], v[10:11]
	v_add_f32_e32 v18, v22, v23
	v_pk_fma_f32 v[16:17], v[12:13], v[110:111], v[12:13]
	v_pk_fma_f32 v[14:15], v[20:21], v[112:113], v[14:15] op_sel_hi:[0,1,1]
	v_add_f32_dpp v18, v18, v18 quad_perm:[1,0,3,2] row_mask:0xf bank_mask:0xf bound_ctrl:1
	v_pk_fma_f32 v[16:17], v[20:21], v[114:115], v[16:17] op_sel_hi:[0,1,1]
	v_pk_mul_f32 v[24:25], v[10:11], v[104:105]
	v_add_f32_dpp v18, v18, v18 quad_perm:[2,3,0,1] row_mask:0xf bank_mask:0xf bound_ctrl:1
	v_pk_fma_f32 v[24:25], v[12:13], v[106:107], v[24:25]
	s_waitcnt lgkmcnt(5)
	ds_read_b128 v[88:91], v46 offset:1536
	v_add_f32_dpp v18, v18, v18 row_ror:4 row_mask:0xf bank_mask:0xf bound_ctrl:1
	ds_read_b128 v[100:103], v46 offset:13824
	v_add_f32_e32 v28, v24, v25
	ds_read_b128 v[92:95], v46 offset:5632
	v_add_f32_dpp v18, v18, v18 row_ror:8 row_mask:0xf bank_mask:0xf bound_ctrl:1
	ds_read_b128 v[96:99], v46 offset:9728
	ds_read_b128 v[104:107], v46 offset:17920
	v_pk_fma_f32 v[10:11], v[18:19], v[116:117], v[14:15] op_sel_hi:[0,1,1]
	v_pk_fma_f32 v[12:13], v[18:19], v[118:119], v[16:17] op_sel_hi:[0,1,1]
	v_mov_b32_dpp v20, v42 row_newbcast:4 row_mask:0xf bank_mask:0xf
	v_pk_mul_f32 v[22:23], v[10:11], v[60:61]
	v_pk_fma_f32 v[22:23], v[12:13], v[62:63], v[22:23]
	v_pk_fma_f32 v[14:15], v[10:11], v[48:49], v[10:11]
	v_add_f32_e32 v18, v22, v23
	v_pk_fma_f32 v[16:17], v[12:13], v[50:51], v[12:13]
	v_pk_fma_f32 v[14:15], v[20:21], v[52:53], v[14:15] op_sel_hi:[0,1,1]
	v_add_f32_dpp v18, v18, v18 quad_perm:[1,0,3,2] row_mask:0xf bank_mask:0xf bound_ctrl:1
	v_pk_fma_f32 v[16:17], v[20:21], v[54:55], v[16:17] op_sel_hi:[0,1,1]
	v_pk_mul_f32 v[24:25], v[10:11], v[124:125]
	v_add_f32_dpp v18, v18, v18 quad_perm:[2,3,0,1] row_mask:0xf bank_mask:0xf bound_ctrl:1
	v_pk_fma_f32 v[24:25], v[12:13], v[126:127], v[24:25]
	s_waitcnt lgkmcnt(5)
	ds_read_b128 v[108:111], v46 offset:1792
	v_add_f32_dpp v18, v18, v18 row_ror:4 row_mask:0xf bank_mask:0xf bound_ctrl:1
	ds_read_b128 v[120:123], v46 offset:14080
	v_add_f32_e32 v29, v24, v25
	ds_read_b128 v[112:115], v46 offset:5888
	v_add_f32_dpp v18, v18, v18 row_ror:8 row_mask:0xf bank_mask:0xf bound_ctrl:1
	ds_read_b128 v[116:119], v46 offset:9984
	ds_read_b128 v[124:127], v46 offset:18176
	v_pk_fma_f32 v[10:11], v[18:19], v[56:57], v[14:15] op_sel_hi:[0,1,1]
	v_pk_fma_f32 v[12:13], v[18:19], v[58:59], v[16:17] op_sel_hi:[0,1,1]
	v_mov_b32_dpp v20, v42 row_newbcast:5 row_mask:0xf bank_mask:0xf
	v_pk_mul_f32 v[22:23], v[10:11], v[80:81]
	v_pk_fma_f32 v[22:23], v[12:13], v[82:83], v[22:23]
	v_pk_fma_f32 v[14:15], v[10:11], v[68:69], v[10:11]
	v_add_f32_e32 v18, v22, v23
	v_pk_fma_f32 v[16:17], v[12:13], v[70:71], v[12:13]
	v_pk_fma_f32 v[14:15], v[20:21], v[72:73], v[14:15] op_sel_hi:[0,1,1]
	v_add_f32_dpp v18, v18, v18 quad_perm:[1,0,3,2] row_mask:0xf bank_mask:0xf bound_ctrl:1
	v_pk_fma_f32 v[16:17], v[20:21], v[74:75], v[16:17] op_sel_hi:[0,1,1]
	v_pk_mul_f32 v[24:25], v[10:11], v[64:65]
	v_add_f32_dpp v18, v18, v18 quad_perm:[2,3,0,1] row_mask:0xf bank_mask:0xf bound_ctrl:1
	v_pk_fma_f32 v[24:25], v[12:13], v[66:67], v[24:25]
	s_waitcnt lgkmcnt(5)
	ds_read_b128 v[48:51], v46 offset:2048
	v_add_f32_dpp v18, v18, v18 row_ror:4 row_mask:0xf bank_mask:0xf bound_ctrl:1
	ds_read_b128 v[60:63], v46 offset:14336
	v_add_f32_e32 v30, v24, v25
	ds_read_b128 v[52:55], v46 offset:6144
	v_add_f32_dpp v18, v18, v18 row_ror:8 row_mask:0xf bank_mask:0xf bound_ctrl:1
	ds_read_b128 v[56:59], v46 offset:10240
	ds_read_b128 v[64:67], v46 offset:18432
	v_pk_fma_f32 v[10:11], v[18:19], v[76:77], v[14:15] op_sel_hi:[0,1,1]
	v_pk_fma_f32 v[12:13], v[18:19], v[78:79], v[16:17] op_sel_hi:[0,1,1]
	v_mov_b32_dpp v20, v42 row_newbcast:6 row_mask:0xf bank_mask:0xf
	v_pk_mul_f32 v[22:23], v[10:11], v[100:101]
	v_pk_fma_f32 v[22:23], v[12:13], v[102:103], v[22:23]
	v_pk_fma_f32 v[14:15], v[10:11], v[88:89], v[10:11]
	v_add_f32_e32 v18, v22, v23
	v_pk_fma_f32 v[16:17], v[12:13], v[90:91], v[12:13]
	v_pk_fma_f32 v[14:15], v[20:21], v[92:93], v[14:15] op_sel_hi:[0,1,1]
	v_add_f32_dpp v18, v18, v18 quad_perm:[1,0,3,2] row_mask:0xf bank_mask:0xf bound_ctrl:1
	v_pk_fma_f32 v[16:17], v[20:21], v[94:95], v[16:17] op_sel_hi:[0,1,1]
	v_pk_mul_f32 v[24:25], v[10:11], v[84:85]
	v_add_f32_dpp v18, v18, v18 quad_perm:[2,3,0,1] row_mask:0xf bank_mask:0xf bound_ctrl:1
	v_pk_fma_f32 v[24:25], v[12:13], v[86:87], v[24:25]
	s_waitcnt lgkmcnt(5)
; __device__ __forceinline__ float row_sum16(float v) { v += __shfl_xor(v, 1); v += __shfl_xor(v, 2); v += __shfl_xor(v, 4); v += __shfl_xor(v, 8); return v; }
; __device__ __forceinline__ float row_sum16(float v) { v += dppf<0xB1>(v); v += dppf<0x4E>(v); v += dppf<0x124>(v); v += dppf<0x128>(v); return v; }
; #define RW_LOAD(slot, step) do { const size_t ro_ = (size_t)row_of(step) * RWW; \
;       s_ok[slot] = *(const h16x8*)((p_rec + ro_ * 3) + urec); s_b[slot] = *(const h16x4*)((p_rec + ro_ * 3) + urec + 8); \
;       s_kr[slot] = *(const h16x8*)((p_sh + ro_ * 2) + ush); s_v[slot] = (p_v + ro_)[uvoff]; } while (0)
; template <int VAR>
; __device__ __forceinline__ void ph_rw_scan(const Params& P) {
;     ...
; #pragma unroll
;       for (int uu = 0; uu < RW_U; ++uu) {
;         const float vv = (float)s_v[uu];
;         const u32x4 p_ok = __builtin_bit_cast(u32x4, s_ok[uu]), p_kr = __builtin_bit_cast(u32x4, s_kr[uu]);
;         const u32x2 p_bb = __builtin_bit_cast(u32x2, s_b[uu]);
;         const unsigned om0 = p_ok[0], om1 = p_ok[1], kd0 = p_ok[2], kd1 = p_ok[3];
;         const unsigned kk0 = p_kr[0], kk1 = p_kr[1], r0_ = p_kr[2], r1_ = p_kr[3];
;         const unsigned b0_ = p_bb[0], b1_ = p_bb[1];
;         float sa = fmix_lo(S[0], kk0, 0.f); sa = fmix_hi(S[1], kk0, sa);
;         float sb = fmix_lo(S[2], kk1, 0.f); sb = fmix_hi(S[3], kk1, sb);
;         sa = row_sum16(sa + sb);
;         S[0] = fmix_lo(S[0], om0, S[0]); S[1] = fmix_hi(S[1], om0, S[1]); S[2] = fmix_lo(S[2], om1, S[2]); S[3] = fmix_hi(S[3], om1, S[3]);
;         S[0] = fmix_lo(sa, b0_, S[0]); S[1] = fmix_hi(sa, b0_, S[1]); S[2] = fmix_lo(sa, b1_, S[2]); S[3] = fmix_hi(sa, b1_, S[3]);
;         S[0] = fmix_lo(vv, kd0, S[0]); S[1] = fmix_hi(vv, kd0, S[1]); S[2] = fmix_lo(vv, kd1, S[2]); S[3] = fmix_hi(vv, kd1, S[3]);
;         float y = fmix_lo(S[0], r0_, 0.f); y = fmix_hi(S[1], r0_, y);
;         float y2 = fmix_lo(S[2], r1_, 0.f); y2 = fmix_hi(S[3], r1_, y2);
;         y += y2;
;         if (VAR == 0 && islat) {
;           y = row_sum16(y);
;           if (q == 0) yout[((size_t)dir * NL + row_of(t0 + uu)) * RWW + hh * 64 + vrow] = (h16)y;
;         }
;         if (VAR != 0) asm volatile("" :: "v"(y));
;         const int nstep = t0 + uu + RW_U < RW_NS ? t0 + uu + RW_U : RW_NS - 1;
;         if (VAR != 2) RW_LOAD(uu, nstep);
	ds_read_b128 v[68:71], v46 offset:2304
	v_add_f32_dpp v18, v18, v18 row_ror:4 row_mask:0xf bank_mask:0xf bound_ctrl:1
	ds_read_b128 v[80:83], v46 offset:14592
	v_add_f32_e32 v31, v24, v25
	ds_read_b128 v[72:75], v46 offset:6400
	v_add_f32_dpp v18, v18, v18 row_ror:8 row_mask:0xf bank_mask:0xf bound_ctrl:1
	ds_read_b128 v[76:79], v46 offset:10496
	ds_read_b128 v[84:87], v46 offset:18688
	v_pk_fma_f32 v[10:11], v[18:19], v[96:97], v[14:15] op_sel_hi:[0,1,1]
	v_pk_fma_f32 v[12:13], v[18:19], v[98:99], v[16:17] op_sel_hi:[0,1,1]
	v_mov_b32_dpp v20, v42 row_newbcast:7 row_mask:0xf bank_mask:0xf
	v_pk_mul_f32 v[22:23], v[10:11], v[120:121]
	v_pk_fma_f32 v[22:23], v[12:13], v[122:123], v[22:23]
	v_pk_fma_f32 v[14:15], v[10:11], v[108:109], v[10:11]
	v_add_f32_e32 v18, v22, v23
	v_pk_fma_f32 v[16:17], v[12:13], v[110:111], v[12:13]
	v_pk_fma_f32 v[14:15], v[20:21], v[112:113], v[14:15] op_sel_hi:[0,1,1]
	v_add_f32_dpp v18, v18, v18 quad_perm:[1,0,3,2] row_mask:0xf bank_mask:0xf bound_ctrl:1
	v_pk_fma_f32 v[16:17], v[20:21], v[114:115], v[16:17] op_sel_hi:[0,1,1]
	v_pk_mul_f32 v[24:25], v[10:11], v[104:105]
	v_add_f32_dpp v18, v18, v18 quad_perm:[2,3,0,1] row_mask:0xf bank_mask:0xf bound_ctrl:1
	v_pk_fma_f32 v[24:25], v[12:13], v[106:107], v[24:25]
	s_waitcnt lgkmcnt(5)
	ds_read_b128 v[88:91], v46 offset:2560
	v_add_f32_dpp v18, v18, v18 row_ror:4 row_mask:0xf bank_mask:0xf bound_ctrl:1
	ds_read_b128 v[100:103], v46 offset:14848
	v_add_f32_e32 v32, v24, v25
	ds_read_b128 v[92:95], v46 offset:6656
	v_add_f32_dpp v18, v18, v18 row_ror:8 row_mask:0xf bank_mask:0xf bound_ctrl:1
	ds_read_b128 v[96:99], v46 offset:10752
	ds_read_b128 v[104:107], v46 offset:18944
	v_pk_fma_f32 v[10:11], v[18:19], v[116:117], v[14:15] op_sel_hi:[0,1,1]
	v_pk_fma_f32 v[12:13], v[18:19], v[118:119], v[16:17] op_sel_hi:[0,1,1]
	v_mov_b32_dpp v20, v42 row_newbcast:8 row_mask:0xf bank_mask:0xf
	v_pk_mul_f32 v[22:23], v[10:11], v[60:61]
	v_pk_fma_f32 v[22:23], v[12:13], v[62:63], v[22:23]
	v_pk_fma_f32 v[14:15], v[10:11], v[48:49], v[10:11]
	v_add_f32_e32 v18, v22, v23
	v_pk_fma_f32 v[16:17], v[12:13], v[50:51], v[12:13]
	v_pk_fma_f32 v[14:15], v[20:21], v[52:53], v[14:15] op_sel_hi:[0,1,1]
	v_add_f32_dpp v18, v18, v18 quad_perm:[1,0,3,2] row_mask:0xf bank_mask:0xf bound_ctrl:1
	v_pk_fma_f32 v[16:17], v[20:21], v[54:55], v[16:17] op_sel_hi:[0,1,1]
	v_pk_mul_f32 v[24:25], v[10:11], v[124:125]
	v_add_f32_dpp v18, v18, v18 quad_perm:[2,3,0,1] row_mask:0xf bank_mask:0xf bound_ctrl:1
	v_pk_fma_f32 v[24:25], v[12:13], v[126:127], v[24:25]
	s_waitcnt lgkmcnt(5)
	ds_read_b128 v[108:111], v46 offset:2816
	v_add_f32_dpp v18, v18, v18 row_ror:4 row_mask:0xf bank_mask:0xf bound_ctrl:1
	ds_read_b128 v[120:123], v46 offset:15104
	v_add_f32_e32 v33, v24, v25
	ds_read_b128 v[112:115], v46 offset:6912
	v_add_f32_dpp v18, v18, v18 row_ror:8 row_mask:0xf bank_mask:0xf bound_ctrl:1
	ds_read_b128 v[116:119], v46 offset:11008
	ds_read_b128 v[124:127], v46 offset:19200
	v_pk_fma_f32 v[10:11], v[18:19], v[56:57], v[14:15] op_sel_hi:[0,1,1]
	v_pk_fma_f32 v[12:13], v[18:19], v[58:59], v[16:17] op_sel_hi:[0,1,1]
	v_mov_b32_dpp v20, v42 row_newbcast:9 row_mask:0xf bank_mask:0xf
	v_pk_mul_f32 v[22:23], v[10:11], v[80:81]
	v_pk_fma_f32 v[22:23], v[12:13], v[82:83], v[22:23]
	v_pk_fma_f32 v[14:15], v[10:11], v[68:69], v[10:11]
	v_add_f32_e32 v18, v22, v23
	v_pk_fma_f32 v[16:17], v[12:13], v[70:71], v[12:13]
	v_pk_fma_f32 v[14:15], v[20:21], v[72:73], v[14:15] op_sel_hi:[0,1,1]
	v_add_f32_dpp v18, v18, v18 quad_perm:[1,0,3,2] row_mask:0xf bank_mask:0xf bound_ctrl:1
	v_pk_fma_f32 v[16:17], v[20:21], v[74:75], v[16:17] op_sel_hi:[0,1,1]
	v_pk_mul_f32 v[24:25], v[10:11], v[64:65]
	v_add_f32_dpp v18, v18, v18 quad_perm:[2,3,0,1] row_mask:0xf bank_mask:0xf bound_ctrl:1
	v_pk_fma_f32 v[24:25], v[12:13], v[66:67], v[24:25]
	s_waitcnt lgkmcnt(5)
	ds_read_b128 v[48:51], v46 offset:3072
	v_add_f32_dpp v18, v18, v18 row_ror:4 row_mask:0xf bank_mask:0xf bound_ctrl:1
	ds_read_b128 v[60:63], v46 offset:15360
	v_add_f32_e32 v34, v24, v25
	ds_read_b128 v[52:55], v46 offset:7168
	v_add_f32_dpp v18, v18, v18 row_ror:8 row_mask:0xf bank_mask:0xf bound_ctrl:1
	ds_read_b128 v[56:59], v46 offset:11264
	ds_read_b128 v[64:67], v46 offset:19456
	v_pk_fma_f32 v[10:11], v[18:19], v[76:77], v[14:15] op_sel_hi:[0,1,1]
	v_pk_fma_f32 v[12:13], v[18:19], v[78:79], v[16:17] op_sel_hi:[0,1,1]
	v_mov_b32_dpp v20, v42 row_newbcast:10 row_mask:0xf bank_mask:0xf
	v_pk_mul_f32 v[22:23], v[10:11], v[100:101]
	v_pk_fma_f32 v[22:23], v[12:13], v[102:103], v[22:23]
	v_pk_fma_f32 v[14:15], v[10:11], v[88:89], v[10:11]
	v_add_f32_e32 v18, v22, v23
	v_pk_fma_f32 v[16:17], v[12:13], v[90:91], v[12:13]
	v_pk_fma_f32 v[14:15], v[20:21], v[92:93], v[14:15] op_sel_hi:[0,1,1]
	v_add_f32_dpp v18, v18, v18 quad_perm:[1,0,3,2] row_mask:0xf bank_mask:0xf bound_ctrl:1
	v_pk_fma_f32 v[16:17], v[20:21], v[94:95], v[16:17] op_sel_hi:[0,1,1]
	v_pk_mul_f32 v[24:25], v[10:11], v[84:85]
	v_add_f32_dpp v18, v18, v18 quad_perm:[2,3,0,1] row_mask:0xf bank_mask:0xf bound_ctrl:1
	v_pk_fma_f32 v[24:25], v[12:13], v[86:87], v[24:25]
	s_waitcnt lgkmcnt(5)
; __device__ __forceinline__ float row_sum16(float v) { v += __shfl_xor(v, 1); v += __shfl_xor(v, 2); v += __shfl_xor(v, 4); v += __shfl_xor(v, 8); return v; }
; __device__ __forceinline__ float row_sum16(float v) { v += dppf<0xB1>(v); v += dppf<0x4E>(v); v += dppf<0x124>(v); v += dppf<0x128>(v); return v; }
; #define RW_LOAD(slot, step) do { const size_t ro_ = (size_t)row_of(step) * RWW; \
;       s_ok[slot] = *(const h16x8*)((p_rec + ro_ * 3) + urec); s_b[slot] = *(const h16x4*)((p_rec + ro_ * 3) + urec + 8); \
;       s_kr[slot] = *(const h16x8*)((p_sh + ro_ * 2) + ush); s_v[slot] = (p_v + ro_)[uvoff]; } while (0)
; template <int VAR>
; __device__ __forceinline__ void ph_rw_scan(const Params& P) {
;     ...
; #pragma unroll
;       for (int uu = 0; uu < RW_U; ++uu) {
;         const float vv = (float)s_v[uu];
;         const u32x4 p_ok = __builtin_bit_cast(u32x4, s_ok[uu]), p_kr = __builtin_bit_cast(u32x4, s_kr[uu]);
;         const u32x2 p_bb = __builtin_bit_cast(u32x2, s_b[uu]);
;         const unsigned om0 = p_ok[0], om1 = p_ok[1], kd0 = p_ok[2], kd1 = p_ok[3];
;         const unsigned kk0 = p_kr[0], kk1 = p_kr[1], r0_ = p_kr[2], r1_ = p_kr[3];
;         const unsigned b0_ = p_bb[0], b1_ = p_bb[1];
;         float sa = fmix_lo(S[0], kk0, 0.f); sa = fmix_hi(S[1], kk0, sa);
;         float sb = fmix_lo(S[2], kk1, 0.f); sb = fmix_hi(S[3], kk1, sb);
;         sa = row_sum16(sa + sb);
;         S[0] = fmix_lo(S[0], om0, S[0]); S[1] = fmix_hi(S[1], om0, S[1]); S[2] = fmix_lo(S[2], om1, S[2]); S[3] = fmix_hi(S[3], om1, S[3]);
;         S[0] = fmix_lo(sa, b0_, S[0]); S[1] = fmix_hi(sa, b0_, S[1]); S[2] = fmix_lo(sa, b1_, S[2]); S[3] = fmix_hi(sa, b1_, S[3]);
;         S[0] = fmix_lo(vv, kd0, S[0]); S[1] = fmix_hi(vv, kd0, S[1]); S[2] = fmix_lo(vv, kd1, S[2]); S[3] = fmix_hi(vv, kd1, S[3]);
;         float y = fmix_lo(S[0], r0_, 0.f); y = fmix_hi(S[1], r0_, y);
;         float y2 = fmix_lo(S[2], r1_, 0.f); y2 = fmix_hi(S[3], r1_, y2);
;         y += y2;
;         if (VAR == 0 && islat) {
;           y = row_sum16(y);
;           if (q == 0) yout[((size_t)dir * NL + row_of(t0 + uu)) * RWW + hh * 64 + vrow] = (h16)y;
;         }
;         if (VAR != 0) asm volatile("" :: "v"(y));
;         const int nstep = t0 + uu + RW_U < RW_NS ? t0 + uu + RW_U : RW_NS - 1;
;         if (VAR != 2) RW_LOAD(uu, nstep);
	ds_read_b128 v[68:71], v46 offset:3328
	v_add_f32_dpp v18, v18, v18 row_ror:4 row_mask:0xf bank_mask:0xf bound_ctrl:1
	ds_read_b128 v[80:83], v46 offset:15616
	v_add_f32_e32 v35, v24, v25
	ds_read_b128 v[72:75], v46 offset:7424
	v_add_f32_dpp v18, v18, v18 row_ror:8 row_mask:0xf bank_mask:0xf bound_ctrl:1
	ds_read_b128 v[76:79], v46 offset:11520
	ds_read_b128 v[84:87], v46 offset:19712
	v_pk_fma_f32 v[10:11], v[18:19], v[96:97], v[14:15] op_sel_hi:[0,1,1]
	v_pk_fma_f32 v[12:13], v[18:19], v[98:99], v[16:17] op_sel_hi:[0,1,1]
	v_mov_b32_dpp v20, v42 row_newbcast:11 row_mask:0xf bank_mask:0xf
	v_pk_mul_f32 v[22:23], v[10:11], v[120:121]
	v_pk_fma_f32 v[22:23], v[12:13], v[122:123], v[22:23]
	v_pk_fma_f32 v[14:15], v[10:11], v[108:109], v[10:11]
	v_add_f32_e32 v18, v22, v23
	v_pk_fma_f32 v[16:17], v[12:13], v[110:111], v[12:13]
	v_pk_fma_f32 v[14:15], v[20:21], v[112:113], v[14:15] op_sel_hi:[0,1,1]
	v_add_f32_dpp v18, v18, v18 quad_perm:[1,0,3,2] row_mask:0xf bank_mask:0xf bound_ctrl:1
	v_pk_fma_f32 v[16:17], v[20:21], v[114:115], v[16:17] op_sel_hi:[0,1,1]
	v_pk_mul_f32 v[24:25], v[10:11], v[104:105]
	v_add_f32_dpp v18, v18, v18 quad_perm:[2,3,0,1] row_mask:0xf bank_mask:0xf bound_ctrl:1
	v_pk_fma_f32 v[24:25], v[12:13], v[106:107], v[24:25]
	s_waitcnt lgkmcnt(5)
	ds_read_b128 v[88:91], v46 offset:3584
	v_add_f32_dpp v18, v18, v18 row_ror:4 row_mask:0xf bank_mask:0xf bound_ctrl:1
	ds_read_b128 v[100:103], v46 offset:15872
	v_add_f32_e32 v36, v24, v25
	ds_read_b128 v[92:95], v46 offset:7680
	v_add_f32_dpp v18, v18, v18 row_ror:8 row_mask:0xf bank_mask:0xf bound_ctrl:1
	ds_read_b128 v[96:99], v46 offset:11776
	ds_read_b128 v[104:107], v46 offset:19968
	v_pk_fma_f32 v[10:11], v[18:19], v[116:117], v[14:15] op_sel_hi:[0,1,1]
	v_pk_fma_f32 v[12:13], v[18:19], v[118:119], v[16:17] op_sel_hi:[0,1,1]
	v_mov_b32_dpp v20, v42 row_newbcast:12 row_mask:0xf bank_mask:0xf
	v_pk_mul_f32 v[22:23], v[10:11], v[60:61]
	v_pk_fma_f32 v[22:23], v[12:13], v[62:63], v[22:23]
	v_pk_fma_f32 v[14:15], v[10:11], v[48:49], v[10:11]
	v_add_f32_e32 v18, v22, v23
	v_pk_fma_f32 v[16:17], v[12:13], v[50:51], v[12:13]
	v_pk_fma_f32 v[14:15], v[20:21], v[52:53], v[14:15] op_sel_hi:[0,1,1]
	v_add_f32_dpp v18, v18, v18 quad_perm:[1,0,3,2] row_mask:0xf bank_mask:0xf bound_ctrl:1
	v_pk_fma_f32 v[16:17], v[20:21], v[54:55], v[16:17] op_sel_hi:[0,1,1]
	v_pk_mul_f32 v[24:25], v[10:11], v[124:125]
	v_add_f32_dpp v18, v18, v18 quad_perm:[2,3,0,1] row_mask:0xf bank_mask:0xf bound_ctrl:1
	v_pk_fma_f32 v[24:25], v[12:13], v[126:127], v[24:25]
	s_waitcnt lgkmcnt(5)
	ds_read_b128 v[108:111], v46 offset:3840
	v_add_f32_dpp v18, v18, v18 row_ror:4 row_mask:0xf bank_mask:0xf bound_ctrl:1
	ds_read_b128 v[120:123], v46 offset:16128
	v_add_f32_e32 v37, v24, v25
	ds_read_b128 v[112:115], v46 offset:7936
	v_add_f32_dpp v18, v18, v18 row_ror:8 row_mask:0xf bank_mask:0xf bound_ctrl:1
	ds_read_b128 v[116:119], v46 offset:12032
	ds_read_b128 v[124:127], v46 offset:20224
	v_pk_fma_f32 v[10:11], v[18:19], v[56:57], v[14:15] op_sel_hi:[0,1,1]
	v_pk_fma_f32 v[12:13], v[18:19], v[58:59], v[16:17] op_sel_hi:[0,1,1]
	v_mov_b32_dpp v20, v42 row_newbcast:13 row_mask:0xf bank_mask:0xf
	v_pk_mul_f32 v[22:23], v[10:11], v[80:81]
	v_pk_fma_f32 v[22:23], v[12:13], v[82:83], v[22:23]
	v_pk_fma_f32 v[14:15], v[10:11], v[68:69], v[10:11]
	v_add_f32_e32 v18, v22, v23
	v_pk_fma_f32 v[16:17], v[12:13], v[70:71], v[12:13]
	v_pk_fma_f32 v[14:15], v[20:21], v[72:73], v[14:15] op_sel_hi:[0,1,1]
	v_add_f32_dpp v18, v18, v18 quad_perm:[1,0,3,2] row_mask:0xf bank_mask:0xf bound_ctrl:1
	v_pk_fma_f32 v[16:17], v[20:21], v[74:75], v[16:17] op_sel_hi:[0,1,1]
	v_pk_mul_f32 v[24:25], v[10:11], v[64:65]
	v_add_f32_dpp v18, v18, v18 quad_perm:[2,3,0,1] row_mask:0xf bank_mask:0xf bound_ctrl:1
	v_pk_fma_f32 v[24:25], v[12:13], v[66:67], v[24:25]
	s_waitcnt lgkmcnt(5)
	ds_read_b128 v[48:51], v47
	v_add_f32_dpp v18, v18, v18 row_ror:4 row_mask:0xf bank_mask:0xf bound_ctrl:1
	ds_read_b128 v[60:63], v47 offset:12288
	v_add_f32_e32 v38, v24, v25
	ds_read_b128 v[52:55], v47 offset:4096
	v_add_f32_dpp v18, v18, v18 row_ror:8 row_mask:0xf bank_mask:0xf bound_ctrl:1
	ds_read_b128 v[56:59], v47 offset:8192
	ds_read_b128 v[64:67], v47 offset:16384
	v_pk_fma_f32 v[10:11], v[18:19], v[76:77], v[14:15] op_sel_hi:[0,1,1]
	v_pk_fma_f32 v[12:13], v[18:19], v[78:79], v[16:17] op_sel_hi:[0,1,1]
	v_mov_b32_dpp v20, v42 row_newbcast:14 row_mask:0xf bank_mask:0xf
	v_pk_mul_f32 v[22:23], v[10:11], v[100:101]
	v_pk_fma_f32 v[22:23], v[12:13], v[102:103], v[22:23]
	v_pk_fma_f32 v[14:15], v[10:11], v[88:89], v[10:11]
	v_add_f32_e32 v18, v22, v23
	v_pk_fma_f32 v[16:17], v[12:13], v[90:91], v[12:13]
	v_pk_fma_f32 v[14:15], v[20:21], v[92:93], v[14:15] op_sel_hi:[0,1,1]
	v_add_f32_dpp v18, v18, v18 quad_perm:[1,0,3,2] row_mask:0xf bank_mask:0xf bound_ctrl:1
	v_pk_fma_f32 v[16:17], v[20:21], v[94:95], v[16:17] op_sel_hi:[0,1,1]
	v_pk_mul_f32 v[24:25], v[10:11], v[84:85]
	v_add_f32_dpp v18, v18, v18 quad_perm:[2,3,0,1] row_mask:0xf bank_mask:0xf bound_ctrl:1
	v_pk_fma_f32 v[24:25], v[12:13], v[86:87], v[24:25]
	s_waitcnt lgkmcnt(5)
; __device__ __forceinline__ float row_sum16(float v) { v += __shfl_xor(v, 1); v += __shfl_xor(v, 2); v += __shfl_xor(v, 4); v += __shfl_xor(v, 8); return v; }
; __device__ __forceinline__ float row_sum16(float v) { v += dppf<0xB1>(v); v += dppf<0x4E>(v); v += dppf<0x124>(v); v += dppf<0x128>(v); return v; }
; #define RW_LOAD(slot, step) do { const size_t ro_ = (size_t)row_of(step) * RWW; \
;       s_ok[slot] = *(const h16x8*)((p_rec + ro_ * 3) + urec); s_b[slot] = *(const h16x4*)((p_rec + ro_ * 3) + urec + 8); \
;       s_kr[slot] = *(const h16x8*)((p_sh + ro_ * 2) + ush); s_v[slot] = (p_v + ro_)[uvoff]; } while (0)
; template <int VAR>
; __device__ __forceinline__ void ph_rw_scan(const Params& P) {
;     ...
; #pragma unroll
;       for (int uu = 0; uu < RW_U; ++uu) {
;         const float vv = (float)s_v[uu];
;         const u32x4 p_ok = __builtin_bit_cast(u32x4, s_ok[uu]), p_kr = __builtin_bit_cast(u32x4, s_kr[uu]);
;         const u32x2 p_bb = __builtin_bit_cast(u32x2, s_b[uu]);
;         const unsigned om0 = p_ok[0], om1 = p_ok[1], kd0 = p_ok[2], kd1 = p_ok[3];
;         const unsigned kk0 = p_kr[0], kk1 = p_kr[1], r0_ = p_kr[2], r1_ = p_kr[3];
;         const unsigned b0_ = p_bb[0], b1_ = p_bb[1];
;         float sa = fmix_lo(S[0], kk0, 0.f); sa = fmix_hi(S[1], kk0, sa);
;         float sb = fmix_lo(S[2], kk1, 0.f); sb = fmix_hi(S[3], kk1, sb);
;         sa = row_sum16(sa + sb);
;         S[0] = fmix_lo(S[0], om0, S[0]); S[1] = fmix_hi(S[1], om0, S[1]); S[2] = fmix_lo(S[2], om1, S[2]); S[3] = fmix_hi(S[3], om1, S[3]);
;         S[0] = fmix_lo(sa, b0_, S[0]); S[1] = fmix_hi(sa, b0_, S[1]); S[2] = fmix_lo(sa, b1_, S[2]); S[3] = fmix_hi(sa, b1_, S[3]);
;         S[0] = fmix_lo(vv, kd0, S[0]); S[1] = fmix_hi(vv, kd0, S[1]); S[2] = fmix_lo(vv, kd1, S[2]); S[3] = fmix_hi(vv, kd1, S[3]);
;         float y = fmix_lo(S[0], r0_, 0.f); y = fmix_hi(S[1], r0_, y);
;         float y2 = fmix_lo(S[2], r1_, 0.f); y2 = fmix_hi(S[3], r1_, y2);
;         y += y2;
;         if (VAR == 0 && islat) {
;           y = row_sum16(y);
;           if (q == 0) yout[((size_t)dir * NL + row_of(t0 + uu)) * RWW + hh * 64 + vrow] = (h16)y;
;         }
;         if (VAR != 0) asm volatile("" :: "v"(y));
;         const int nstep = t0 + uu + RW_U < RW_NS ? t0 + uu + RW_U : RW_NS - 1;
;         if (VAR != 2) RW_LOAD(uu, nstep);
	ds_read_b128 v[68:71], v47 offset:256
	v_add_f32_dpp v18, v18, v18 row_ror:4 row_mask:0xf bank_mask:0xf bound_ctrl:1
	ds_read_b128 v[80:83], v47 offset:12544
	v_add_f32_e32 v39, v24, v25
	ds_read_b128 v[72:75], v47 offset:4352
	v_add_f32_dpp v18, v18, v18 row_ror:8 row_mask:0xf bank_mask:0xf bound_ctrl:1
	ds_read_b128 v[76:79], v47 offset:8448
	ds_read_b128 v[84:87], v47 offset:16640
	v_pk_fma_f32 v[10:11], v[18:19], v[96:97], v[14:15] op_sel_hi:[0,1,1]
	v_pk_fma_f32 v[12:13], v[18:19], v[98:99], v[16:17] op_sel_hi:[0,1,1]
	v_mov_b32_dpp v20, v42 row_newbcast:15 row_mask:0xf bank_mask:0xf
	v_pk_mul_f32 v[22:23], v[10:11], v[120:121]
	v_pk_fma_f32 v[22:23], v[12:13], v[122:123], v[22:23]
	v_pk_fma_f32 v[14:15], v[10:11], v[108:109], v[10:11]
	v_add_f32_e32 v18, v22, v23
	v_pk_fma_f32 v[16:17], v[12:13], v[110:111], v[12:13]
	v_pk_fma_f32 v[14:15], v[20:21], v[112:113], v[14:15] op_sel_hi:[0,1,1]
	v_add_f32_dpp v18, v18, v18 quad_perm:[1,0,3,2] row_mask:0xf bank_mask:0xf bound_ctrl:1
	v_pk_fma_f32 v[16:17], v[20:21], v[114:115], v[16:17] op_sel_hi:[0,1,1]
	v_pk_mul_f32 v[24:25], v[10:11], v[104:105]
	v_add_f32_dpp v18, v18, v18 quad_perm:[2,3,0,1] row_mask:0xf bank_mask:0xf bound_ctrl:1
	v_pk_fma_f32 v[24:25], v[12:13], v[106:107], v[24:25]
	s_waitcnt lgkmcnt(5)
	ds_read_b128 v[88:91], v47 offset:512
	v_add_f32_dpp v18, v18, v18 row_ror:4 row_mask:0xf bank_mask:0xf bound_ctrl:1
	ds_read_b128 v[100:103], v47 offset:12800
	v_add_f32_e32 v40, v24, v25
	ds_read_b128 v[92:95], v47 offset:4608
	v_add_f32_dpp v18, v18, v18 row_ror:8 row_mask:0xf bank_mask:0xf bound_ctrl:1
	ds_read_b128 v[96:99], v47 offset:8704
	ds_read_b128 v[104:107], v47 offset:16896
	v_pk_fma_f32 v[10:11], v[18:19], v[116:117], v[14:15] op_sel_hi:[0,1,1]
	v_pk_fma_f32 v[12:13], v[18:19], v[118:119], v[16:17] op_sel_hi:[0,1,1]
	s_waitcnt vmcnt(0)
	v_cvt_f32_f16_e32 v42, v43
	s_mov_b32 s26, s27
	s_add_u32 s27, s27, 20480
	s_cmp_eq_u32 s27, 61440
	s_cselect_b32 s27, 0, s27
	v_add_u32_e32 v46, s26, v8
	v_add_u32_e32 v47, s27, v8
	s_barrier
	s_add_u32 s3, s3, 1
	s_cmp_lt_u32 s3, 0x410
	s_cbranch_scc1 .Lscan_loop_d0
	v_pk_mul_f32 v[24:25], v[10:11], v[124:125]
	v_pk_fma_f32 v[24:25], v[12:13], v[126:127], v[24:25]
	v_add_f32_e32 v41, v24, v25
	s_nop 1
	v_add_f32_dpp v26, v26, v26 row_ror:8 row_mask:0xf bank_mask:0xf bound_ctrl:1
	v_add_f32_dpp v27, v27, v27 row_ror:8 row_mask:0xf bank_mask:0xf bound_ctrl:1
	v_add_f32_dpp v28, v28, v28 row_ror:8 row_mask:0xf bank_mask:0xf bound_ctrl:1
	v_add_f32_dpp v29, v29, v29 row_ror:8 row_mask:0xf bank_mask:0xf bound_ctrl:1
	v_add_f32_dpp v30, v30, v30 row_ror:8 row_mask:0xf bank_mask:0xf bound_ctrl:1
	v_add_f32_dpp v31, v31, v31 row_ror:8 row_mask:0xf bank_mask:0xf bound_ctrl:1
	v_add_f32_dpp v32, v32, v32 row_ror:8 row_mask:0xf bank_mask:0xf bound_ctrl:1
	v_add_f32_dpp v33, v33, v33 row_ror:8 row_mask:0xf bank_mask:0xf bound_ctrl:1
	v_add_f32_dpp v26, v34, v34 row_ror:8 row_mask:0xf bank_mask:0xc bound_ctrl:1
	v_add_f32_dpp v27, v35, v35 row_ror:8 row_mask:0xf bank_mask:0xc bound_ctrl:1
	v_add_f32_dpp v28, v36, v36 row_ror:8 row_mask:0xf bank_mask:0xc bound_ctrl:1
	v_add_f32_dpp v29, v37, v37 row_ror:8 row_mask:0xf bank_mask:0xc bound_ctrl:1
	v_add_f32_dpp v30, v38, v38 row_ror:8 row_mask:0xf bank_mask:0xc bound_ctrl:1
	v_add_f32_dpp v31, v39, v39 row_ror:8 row_mask:0xf bank_mask:0xc bound_ctrl:1
	v_add_f32_dpp v32, v40, v40 row_ror:8 row_mask:0xf bank_mask:0xc bound_ctrl:1
	v_add_f32_dpp v33, v41, v41 row_ror:8 row_mask:0xf bank_mask:0xc bound_ctrl:1
	v_add_f32_dpp v26, v26, v26 row_half_mirror row_mask:0xf bank_mask:0xf bound_ctrl:1
	v_add_f32_dpp v27, v27, v27 row_half_mirror row_mask:0xf bank_mask:0xf bound_ctrl:1
	v_add_f32_dpp v28, v28, v28 row_half_mirror row_mask:0xf bank_mask:0xf bound_ctrl:1
	v_add_f32_dpp v29, v29, v29 row_half_mirror row_mask:0xf bank_mask:0xf bound_ctrl:1
	v_add_f32_dpp v26, v30, v30 row_half_mirror row_mask:0xf bank_mask:0xa bound_ctrl:1
	v_add_f32_dpp v27, v31, v31 row_half_mirror row_mask:0xf bank_mask:0xa bound_ctrl:1
	v_add_f32_dpp v28, v32, v32 row_half_mirror row_mask:0xf bank_mask:0xa bound_ctrl:1
	v_add_f32_dpp v29, v33, v33 row_half_mirror row_mask:0xf bank_mask:0xa bound_ctrl:1
	v_add_f32_dpp v26, v26, v26 quad_perm:[1,0,3,2] row_mask:0xf bank_mask:0xf bound_ctrl:1
	v_add_f32_dpp v27, v27, v27 quad_perm:[1,0,3,2] row_mask:0xf bank_mask:0xf bound_ctrl:1
	v_add_f32_dpp v28, v28, v28 quad_perm:[1,0,3,2] row_mask:0xf bank_mask:0xf bound_ctrl:1
	v_add_f32_dpp v29, v29, v29 quad_perm:[1,0,3,2] row_mask:0xf bank_mask:0xf bound_ctrl:1
	v_add_f32_dpp v26, v26, v26 quad_perm:[2,3,0,1] row_mask:0xf bank_mask:0xf bound_ctrl:1
	v_add_f32_dpp v27, v27, v27 quad_perm:[2,3,0,1] row_mask:0xf bank_mask:0xf bound_ctrl:1
	v_add_f32_dpp v28, v28, v28 quad_perm:[2,3,0,1] row_mask:0xf bank_mask:0xf bound_ctrl:1
	v_add_f32_dpp v29, v29, v29 quad_perm:[2,3,0,1] row_mask:0xf bank_mask:0xf bound_ctrl:1
	v_cndmask_b32_e64 v26, v26, v27, s[20:21]
	v_cndmask_b32_e64 v26, v26, v28, s[22:23]
	v_cndmask_b32_e64 v26, v26, v29, s[24:25]
	v_cvt_f16_f32_e32 v45, v26
	global_store_short v44, v45, s[12:13]
	s_add_u32 s12, s12, 0x8000
	s_addc_u32 s13, s13, 0
	s_waitcnt vmcnt(0) lgkmcnt(0)
	s_branch .Lscan_next
; __device__ __forceinline__ float row_sum16(float v) { v += __shfl_xor(v, 1); v += __shfl_xor(v, 2); v += __shfl_xor(v, 4); v += __shfl_xor(v, 8); return v; }
; template <int VAR>
; __device__ __forceinline__ void ph_rw_scan(const Params& P) {
;     ...
;     const int rg = wu % 16, hh = (wu / 16) % RW_H, b = (wu / (16 * RW_H)) % BATCH, dir = wu / (16 * RW_H * BATCH);
;     const int vrow = rg * 4 + rl;
;     ...
;     const unsigned g_ = (unsigned)(hh * 16 + q);
;     const unsigned uvoff = (unsigned)(hh * 64 + vrow), urec = g_ * 12u, ush = g_ * 8u;
;     h16x8 s_ok[RW_U], s_kr[RW_U]; h16x4 s_b[RW_U]; h16 s_v[RW_U];
;     auto row_of = [&](int step) -> int {
;       if (step < CTX_LEN) return NL + b * CTX_LEN + (dir == 0 ? step : CTX_LEN - 1 - step);
;       const int s = step - CTX_LEN; return b * SEQ + (dir == 0 ? s : SEQ - 1 - s);
;     };
;     ...
; #pragma unroll
;     for (int uu = 0; uu < RW_U; ++uu) RW_LOAD(uu, uu);
;     float S[4] = {0.f, 0.f, 0.f, 0.f};
;     for (int t0 = 0; t0 < RW_NS; t0 += RW_U) {
;       const bool islat = t0 >= CTX_LEN;
; #pragma unroll
;       for (int uu = 0; uu < RW_U; ++uu) {
;         const float vv = (float)s_v[uu];
;         const u32x4 p_ok = __builtin_bit_cast(u32x4, s_ok[uu]), p_kr = __builtin_bit_cast(u32x4, s_kr[uu]);
;         const u32x2 p_bb = __builtin_bit_cast(u32x2, s_b[uu]);
;         const unsigned om0 = p_ok[0], om1 = p_ok[1], kd0 = p_ok[2], kd1 = p_ok[3];
;         const unsigned kk0 = p_kr[0], kk1 = p_kr[1], r0_ = p_kr[2], r1_ = p_kr[3];
;         const unsigned b0_ = p_bb[0], b1_ = p_bb[1];
;         float sa = fmix_lo(S[0], kk0, 0.f); sa = fmix_hi(S[1], kk0, sa);
;         float sb = fmix_lo(S[2], kk1, 0.f); sb = fmix_hi(S[3], kk1, sb);
;         sa = row_sum16(sa + sb);
;         S[0] = fmix_lo(S[0], om0, S[0]); S[1] = fmix_hi(S[1], om0, S[1]); S[2] = fmix_lo(S[2], om1, S[2]); S[3] = fmix_hi(S[3], om1, S[3]);
;         S[0] = fmix_lo(sa, b0_, S[0]); S[1] = fmix_hi(sa, b0_, S[1]); S[2] = fmix_lo(sa, b1_, S[2]); S[3] = fmix_hi(sa, b1_, S[3]);
;         S[0] = fmix_lo(vv, kd0, S[0]); S[1] = fmix_hi(vv, kd0, S[1]); S[2] = fmix_lo(vv, kd1, S[2]); S[3] = fmix_hi(vv, kd1, S[3]);
;         float y = fmix_lo(S[0], r0_, 0.f); y = fmix_hi(S[1], r0_, y);
;         float y2 = fmix_lo(S[2], r1_, 0.f); y2 = fmix_hi(S[3], r1_, y2);
.Lscan_dir1:
	v_sub_u32_e32 v45, 15, v2
	v_lshlrev_b32_e32 v44, 11, v45
	v_add_u32_e32 v44, v44, v7
	s_lshl_b32 s30, s28, 8
	s_add_u32 s30, s30, 0x80f0
	s_lshl_b32 s31, s28, 14
	s_add_u32 s31, s31, 0x3ff0
	s_mul_i32 s3, s30, 0x800
	s_add_u32 s10, s4, s3
	s_addc_u32 s11, s5, 0
	s_add_u32 s10, s10, 0x3bc14000
	s_addc_u32 s11, s11, 0
	s_mul_i32 s3, s31, 0x800
	s_add_u32 s18, s4, s3
	s_addc_u32 s19, s5, 0
	s_add_u32 s18, s18, 0x3bc14000
	s_addc_u32 s19, s19, 0
	s_mul_i32 s3, s31, 0x800
	s_add_u32 s12, s4, s3
	s_addc_u32 s13, s5, 0
	s_add_u32 s12, s12, 0x1a0cc000
	s_addc_u32 s13, s13, 0
	v_mov_b32_e32 v10, 0
	v_mov_b32_e32 v11, 0
	v_mov_b32_e32 v12, 0
	v_mov_b32_e32 v13, 0
	global_load_ushort v42, v44, s[10:11]
	s_mov_b32 s26, 0
	s_mov_b32 s27, 20480
	v_add_u32_e32 v46, s26, v8
	v_add_u32_e32 v47, s27, v8
	s_waitcnt vmcnt(0) lgkmcnt(0)
	v_cvt_f32_f16_e32 v42, v42
	s_barrier
	ds_read_b128 v[48:51], v46
	ds_read_b128 v[60:63], v46 offset:12288
	ds_read_b128 v[52:55], v46 offset:4096
	ds_read_b128 v[56:59], v46 offset:8192
	ds_read_b128 v[64:67], v46 offset:16384
	ds_read_b128 v[68:71], v46 offset:256
	ds_read_b128 v[80:83], v46 offset:12544
	ds_read_b128 v[72:75], v46 offset:4352
	ds_read_b128 v[76:79], v46 offset:8448
	ds_read_b128 v[84:87], v46 offset:16640
	ds_read_b128 v[88:91], v46 offset:512
	ds_read_b128 v[100:103], v46 offset:12800
	ds_read_b128 v[92:95], v46 offset:4608
	ds_read_b128 v[96:99], v46 offset:8704
	ds_read_b128 v[104:107], v46 offset:16896
	s_mov_b32 s3, 0
	s_waitcnt lgkmcnt(10)
.Lscan_loop_d1:
	v_mov_b32_dpp v20, v42 row_newbcast:0 row_mask:0xf bank_mask:0xf
	v_pk_mul_f32 v[22:23], v[10:11], v[60:61]
	v_pk_fma_f32 v[22:23], v[12:13], v[62:63], v[22:23]
	v_pk_fma_f32 v[14:15], v[10:11], v[48:49], v[10:11]
	v_add_f32_e32 v18, v22, v23
	v_pk_fma_f32 v[16:17], v[12:13], v[50:51], v[12:13]
	v_pk_fma_f32 v[14:15], v[20:21], v[52:53], v[14:15] op_sel_hi:[0,1,1]
	v_add_f32_dpp v18, v18, v18 quad_perm:[1,0,3,2] row_mask:0xf bank_mask:0xf bound_ctrl:1
	v_pk_fma_f32 v[16:17], v[20:21], v[54:55], v[16:17] op_sel_hi:[0,1,1]
	v_pk_mul_f32 v[24:25], v[10:11], v[124:125]
	v_add_f32_dpp v18, v18, v18 quad_perm:[2,3,0,1] row_mask:0xf bank_mask:0xf bound_ctrl:1
	v_pk_fma_f32 v[24:25], v[12:13], v[126:127], v[24:25]
	s_waitcnt lgkmcnt(5)
	ds_read_b128 v[108:111], v46 offset:768
	v_add_f32_dpp v18, v18, v18 row_ror:4 row_mask:0xf bank_mask:0xf bound_ctrl:1
	ds_read_b128 v[120:123], v46 offset:13056
	v_add_f32_e32 v41, v24, v25
	ds_read_b128 v[112:115], v46 offset:4864
	v_add_f32_dpp v18, v18, v18 row_ror:8 row_mask:0xf bank_mask:0xf bound_ctrl:1
	ds_read_b128 v[116:119], v46 offset:8960
	ds_read_b128 v[124:127], v46 offset:17152
	v_pk_fma_f32 v[10:11], v[18:19], v[56:57], v[14:15] op_sel_hi:[0,1,1]
	v_pk_fma_f32 v[12:13], v[18:19], v[58:59], v[16:17] op_sel_hi:[0,1,1]
	s_cmp_eq_u32 s3, 15
	s_cbranch_scc1 .Lscan_vsw_d1
	s_sub_u32 s10, s10, 0x8000
	s_subb_u32 s11, s11, 0
	s_branch .Lscan_vdone_d1

; __device__ __forceinline__ float row_sum16(float v) { v += __shfl_xor(v, 1); v += __shfl_xor(v, 2); v += __shfl_xor(v, 4); v += __shfl_xor(v, 8); return v; }
; __device__ __forceinline__ float row_sum16(float v) { v += dppf<0xB1>(v); v += dppf<0x4E>(v); v += dppf<0x124>(v); v += dppf<0x128>(v); return v; }
; #define RW_LOAD(slot, step) do { const size_t ro_ = (size_t)row_of(step) * RWW; \
;       s_ok[slot] = *(const h16x8*)((p_rec + ro_ * 3) + urec); s_b[slot] = *(const h16x4*)((p_rec + ro_ * 3) + urec + 8); \
;       s_kr[slot] = *(const h16x8*)((p_sh + ro_ * 2) + ush); s_v[slot] = (p_v + ro_)[uvoff]; } while (0)
; template <int VAR>
; __device__ __forceinline__ void ph_rw_scan(const Params& P) {
;     ...
; #pragma unroll
;       for (int uu = 0; uu < RW_U; ++uu) {
;         const float vv = (float)s_v[uu];
;         const u32x4 p_ok = __builtin_bit_cast(u32x4, s_ok[uu]), p_kr = __builtin_bit_cast(u32x4, s_kr[uu]);
;         const u32x2 p_bb = __builtin_bit_cast(u32x2, s_b[uu]);
;         const unsigned om0 = p_ok[0], om1 = p_ok[1], kd0 = p_ok[2], kd1 = p_ok[3];
;         const unsigned kk0 = p_kr[0], kk1 = p_kr[1], r0_ = p_kr[2], r1_ = p_kr[3];
;         const unsigned b0_ = p_bb[0], b1_ = p_bb[1];
;         float sa = fmix_lo(S[0], kk0, 0.f); sa = fmix_hi(S[1], kk0, sa);
;         float sb = fmix_lo(S[2], kk1, 0.f); sb = fmix_hi(S[3], kk1, sb);
;         sa = row_sum16(sa + sb);
;         S[0] = fmix_lo(S[0], om0, S[0]); S[1] = fmix_hi(S[1], om0, S[1]); S[2] = fmix_lo(S[2], om1, S[2]); S[3] = fmix_hi(S[3], om1, S[3]);
;         S[0] = fmix_lo(sa, b0_, S[0]); S[1] = fmix_hi(sa, b0_, S[1]); S[2] = fmix_lo(sa, b1_, S[2]); S[3] = fmix_hi(sa, b1_, S[3]);
;         S[0] = fmix_lo(vv, kd0, S[0]); S[1] = fmix_hi(vv, kd0, S[1]); S[2] = fmix_lo(vv, kd1, S[2]); S[3] = fmix_hi(vv, kd1, S[3]);
;         float y = fmix_lo(S[0], r0_, 0.f); y = fmix_hi(S[1], r0_, y);
;         float y2 = fmix_lo(S[2], r1_, 0.f); y2 = fmix_hi(S[3], r1_, y2);
;         y += y2;
;         if (VAR == 0 && islat) {
;           y = row_sum16(y);
;           if (q == 0) yout[((size_t)dir * NL + row_of(t0 + uu)) * RWW + hh * 64 + vrow] = (h16)y;
;         }
;         if (VAR != 0) asm volatile("" :: "v"(y));
;         const int nstep = t0 + uu + RW_U < RW_NS ? t0 + uu + RW_U : RW_NS - 1;
;         if (VAR != 2) RW_LOAD(uu, nstep);
.Lscan_vdone_d1:
	global_load_ushort v43, v44, s[10:11]
	s_cmp_lt_u32 s3, 17
	s_cbranch_scc1 .Lscan_noy_d1
	v_add_f32_dpp v26, v26, v26 row_ror:8 row_mask:0xf bank_mask:0xf bound_ctrl:1
	v_add_f32_dpp v27, v27, v27 row_ror:8 row_mask:0xf bank_mask:0xf bound_ctrl:1
	v_add_f32_dpp v28, v28, v28 row_ror:8 row_mask:0xf bank_mask:0xf bound_ctrl:1
	v_add_f32_dpp v29, v29, v29 row_ror:8 row_mask:0xf bank_mask:0xf bound_ctrl:1
	v_add_f32_dpp v30, v30, v30 row_ror:8 row_mask:0xf bank_mask:0xf bound_ctrl:1
	v_add_f32_dpp v31, v31, v31 row_ror:8 row_mask:0xf bank_mask:0xf bound_ctrl:1
	v_add_f32_dpp v32, v32, v32 row_ror:8 row_mask:0xf bank_mask:0xf bound_ctrl:1
	v_add_f32_dpp v33, v33, v33 row_ror:8 row_mask:0xf bank_mask:0xf bound_ctrl:1
	v_add_f32_dpp v26, v34, v34 row_ror:8 row_mask:0xf bank_mask:0xc bound_ctrl:1
	v_add_f32_dpp v27, v35, v35 row_ror:8 row_mask:0xf bank_mask:0xc bound_ctrl:1
	v_add_f32_dpp v28, v36, v36 row_ror:8 row_mask:0xf bank_mask:0xc bound_ctrl:1
	v_add_f32_dpp v29, v37, v37 row_ror:8 row_mask:0xf bank_mask:0xc bound_ctrl:1
	v_add_f32_dpp v30, v38, v38 row_ror:8 row_mask:0xf bank_mask:0xc bound_ctrl:1
	v_add_f32_dpp v31, v39, v39 row_ror:8 row_mask:0xf bank_mask:0xc bound_ctrl:1
	v_add_f32_dpp v32, v40, v40 row_ror:8 row_mask:0xf bank_mask:0xc bound_ctrl:1
	v_add_f32_dpp v33, v41, v41 row_ror:8 row_mask:0xf bank_mask:0xc bound_ctrl:1
	v_add_f32_dpp v26, v26, v26 row_half_mirror row_mask:0xf bank_mask:0xf bound_ctrl:1
	v_add_f32_dpp v27, v27, v27 row_half_mirror row_mask:0xf bank_mask:0xf bound_ctrl:1
	v_add_f32_dpp v28, v28, v28 row_half_mirror row_mask:0xf bank_mask:0xf bound_ctrl:1
	v_add_f32_dpp v29, v29, v29 row_half_mirror row_mask:0xf bank_mask:0xf bound_ctrl:1
	v_add_f32_dpp v26, v30, v30 row_half_mirror row_mask:0xf bank_mask:0xa bound_ctrl:1
	v_add_f32_dpp v27, v31, v31 row_half_mirror row_mask:0xf bank_mask:0xa bound_ctrl:1
	v_add_f32_dpp v28, v32, v32 row_half_mirror row_mask:0xf bank_mask:0xa bound_ctrl:1
	v_add_f32_dpp v29, v33, v33 row_half_mirror row_mask:0xf bank_mask:0xa bound_ctrl:1
	v_add_f32_dpp v26, v26, v26 quad_perm:[1,0,3,2] row_mask:0xf bank_mask:0xf bound_ctrl:1
	v_add_f32_dpp v27, v27, v27 quad_perm:[1,0,3,2] row_mask:0xf bank_mask:0xf bound_ctrl:1
	v_add_f32_dpp v28, v28, v28 quad_perm:[1,0,3,2] row_mask:0xf bank_mask:0xf bound_ctrl:1
	v_add_f32_dpp v29, v29, v29 quad_perm:[1,0,3,2] row_mask:0xf bank_mask:0xf bound_ctrl:1
	v_add_f32_dpp v26, v26, v26 quad_perm:[2,3,0,1] row_mask:0xf bank_mask:0xf bound_ctrl:1
	v_add_f32_dpp v27, v27, v27 quad_perm:[2,3,0,1] row_mask:0xf bank_mask:0xf bound_ctrl:1
	v_add_f32_dpp v28, v28, v28 quad_perm:[2,3,0,1] row_mask:0xf bank_mask:0xf bound_ctrl:1
	v_add_f32_dpp v29, v29, v29 quad_perm:[2,3,0,1] row_mask:0xf bank_mask:0xf bound_ctrl:1
	v_cndmask_b32_e64 v26, v26, v27, s[20:21]
	v_cndmask_b32_e64 v26, v26, v28, s[22:23]
	v_cndmask_b32_e64 v26, v26, v29, s[24:25]
	v_cvt_f16_f32_e32 v45, v26
	global_store_short v44, v45, s[12:13]
	s_sub_u32 s12, s12, 0x8000
	s_subb_u32 s13, s13, 0
.Lscan_noy_d1:
	v_mov_b32_dpp v20, v42 row_newbcast:1 row_mask:0xf bank_mask:0xf
	v_pk_mul_f32 v[22:23], v[10:11], v[80:81]
	v_pk_fma_f32 v[22:23], v[12:13], v[82:83], v[22:23]
	v_pk_fma_f32 v[14:15], v[10:11], v[68:69], v[10:11]
	v_add_f32_e32 v18, v22, v23
	v_pk_fma_f32 v[16:17], v[12:13], v[70:71], v[12:13]
	v_pk_fma_f32 v[14:15], v[20:21], v[72:73], v[14:15] op_sel_hi:[0,1,1]
	v_add_f32_dpp v18, v18, v18 quad_perm:[1,0,3,2] row_mask:0xf bank_mask:0xf bound_ctrl:1
	v_pk_fma_f32 v[16:17], v[20:21], v[74:75], v[16:17] op_sel_hi:[0,1,1]
	v_pk_mul_f32 v[24:25], v[10:11], v[64:65]
	v_add_f32_dpp v18, v18, v18 quad_perm:[2,3,0,1] row_mask:0xf bank_mask:0xf bound_ctrl:1
	v_pk_fma_f32 v[24:25], v[12:13], v[66:67], v[24:25]
	s_waitcnt lgkmcnt(5)
	ds_read_b128 v[48:51], v46 offset:1024
	v_add_f32_dpp v18, v18, v18 row_ror:4 row_mask:0xf bank_mask:0xf bound_ctrl:1
	ds_read_b128 v[60:63], v46 offset:13312
	v_add_f32_e32 v26, v24, v25
	ds_read_b128 v[52:55], v46 offset:5120
	v_add_f32_dpp v18, v18, v18 row_ror:8 row_mask:0xf bank_mask:0xf bound_ctrl:1
	ds_read_b128 v[56:59], v46 offset:9216
	ds_read_b128 v[64:67], v46 offset:17408
	v_pk_fma_f32 v[10:11], v[18:19], v[76:77], v[14:15] op_sel_hi:[0,1,1]
	v_pk_fma_f32 v[12:13], v[18:19], v[78:79], v[16:17] op_sel_hi:[0,1,1]
	v_mov_b32_dpp v20, v42 row_newbcast:2 row_mask:0xf bank_mask:0xf
	v_pk_mul_f32 v[22:23], v[10:11], v[100:101]
	v_pk_fma_f32 v[22:23], v[12:13], v[102:103], v[22:23]
	v_pk_fma_f32 v[14:15], v[10:11], v[88:89], v[10:11]
	v_add_f32_e32 v18, v22, v23
	v_pk_fma_f32 v[16:17], v[12:13], v[90:91], v[12:13]
	v_pk_fma_f32 v[14:15], v[20:21], v[92:93], v[14:15] op_sel_hi:[0,1,1]
	v_add_f32_dpp v18, v18, v18 quad_perm:[1,0,3,2] row_mask:0xf bank_mask:0xf bound_ctrl:1
	v_pk_fma_f32 v[16:17], v[20:21], v[94:95], v[16:17] op_sel_hi:[0,1,1]
	v_pk_mul_f32 v[24:25], v[10:11], v[84:85]
	v_add_f32_dpp v18, v18, v18 quad_perm:[2,3,0,1] row_mask:0xf bank_mask:0xf bound_ctrl:1
	v_pk_fma_f32 v[24:25], v[12:13], v[86:87], v[24:25]
	s_waitcnt lgkmcnt(5)
; __device__ __forceinline__ float row_sum16(float v) { v += __shfl_xor(v, 1); v += __shfl_xor(v, 2); v += __shfl_xor(v, 4); v += __shfl_xor(v, 8); return v; }
; __device__ __forceinline__ float row_sum16(float v) { v += dppf<0xB1>(v); v += dppf<0x4E>(v); v += dppf<0x124>(v); v += dppf<0x128>(v); return v; }
; #define RW_LOAD(slot, step) do { const size_t ro_ = (size_t)row_of(step) * RWW; \
;       s_ok[slot] = *(const h16x8*)((p_rec + ro_ * 3) + urec); s_b[slot] = *(const h16x4*)((p_rec + ro_ * 3) + urec + 8); \
;       s_kr[slot] = *(const h16x8*)((p_sh + ro_ * 2) + ush); s_v[slot] = (p_v + ro_)[uvoff]; } while (0)
; template <int VAR>
; __device__ __forceinline__ void ph_rw_scan(const Params& P) {
;     ...
; #pragma unroll
;       for (int uu = 0; uu < RW_U; ++uu) {
;         const float vv = (float)s_v[uu];
;         const u32x4 p_ok = __builtin_bit_cast(u32x4, s_ok[uu]), p_kr = __builtin_bit_cast(u32x4, s_kr[uu]);
;         const u32x2 p_bb = __builtin_bit_cast(u32x2, s_b[uu]);
;         const unsigned om0 = p_ok[0], om1 = p_ok[1], kd0 = p_ok[2], kd1 = p_ok[3];
;         const unsigned kk0 = p_kr[0], kk1 = p_kr[1], r0_ = p_kr[2], r1_ = p_kr[3];
;         const unsigned b0_ = p_bb[0], b1_ = p_bb[1];
;         float sa = fmix_lo(S[0], kk0, 0.f); sa = fmix_hi(S[1], kk0, sa);
;         float sb = fmix_lo(S[2], kk1, 0.f); sb = fmix_hi(S[3], kk1, sb);
;         sa = row_sum16(sa + sb);
;         S[0] = fmix_lo(S[0], om0, S[0]); S[1] = fmix_hi(S[1], om0, S[1]); S[2] = fmix_lo(S[2], om1, S[2]); S[3] = fmix_hi(S[3], om1, S[3]);
;         S[0] = fmix_lo(sa, b0_, S[0]); S[1] = fmix_hi(sa, b0_, S[1]); S[2] = fmix_lo(sa, b1_, S[2]); S[3] = fmix_hi(sa, b1_, S[3]);
;         S[0] = fmix_lo(vv, kd0, S[0]); S[1] = fmix_hi(vv, kd0, S[1]); S[2] = fmix_lo(vv, kd1, S[2]); S[3] = fmix_hi(vv, kd1, S[3]);
;         float y = fmix_lo(S[0], r0_, 0.f); y = fmix_hi(S[1], r0_, y);
;         float y2 = fmix_lo(S[2], r1_, 0.f); y2 = fmix_hi(S[3], r1_, y2);
;         y += y2;
;         if (VAR == 0 && islat) {
;           y = row_sum16(y);
;           if (q == 0) yout[((size_t)dir * NL + row_of(t0 + uu)) * RWW + hh * 64 + vrow] = (h16)y;
;         }
;         if (VAR != 0) asm volatile("" :: "v"(y));
;         const int nstep = t0 + uu + RW_U < RW_NS ? t0 + uu + RW_U : RW_NS - 1;
;         if (VAR != 2) RW_LOAD(uu, nstep);
	ds_read_b128 v[68:71], v46 offset:1280
	v_add_f32_dpp v18, v18, v18 row_ror:4 row_mask:0xf bank_mask:0xf bound_ctrl:1
	ds_read_b128 v[80:83], v46 offset:13568
	v_add_f32_e32 v27, v24, v25
	ds_read_b128 v[72:75], v46 offset:5376
	v_add_f32_dpp v18, v18, v18 row_ror:8 row_mask:0xf bank_mask:0xf bound_ctrl:1
	ds_read_b128 v[76:79], v46 offset:9472
	ds_read_b128 v[84:87], v46 offset:17664
	v_pk_fma_f32 v[10:11], v[18:19], v[96:97], v[14:15] op_sel_hi:[0,1,1]
	v_pk_fma_f32 v[12:13], v[18:19], v[98:99], v[16:17] op_sel_hi:[0,1,1]
	v_mov_b32_dpp v20, v42 row_newbcast:3 row_mask:0xf bank_mask:0xf
	v_pk_mul_f32 v[22:23], v[10:11], v[120:121]
	v_pk_fma_f32 v[22:23], v[12:13], v[122:123], v[22:23]
	v_pk_fma_f32 v[14:15], v[10:11], v[108:109], v[10:11]
	v_add_f32_e32 v18, v22, v23
	v_pk_fma_f32 v[16:17], v[12:13], v[110:111], v[12:13]
	v_pk_fma_f32 v[14:15], v[20:21], v[112:113], v[14:15] op_sel_hi:[0,1,1]
	v_add_f32_dpp v18, v18, v18 quad_perm:[1,0,3,2] row_mask:0xf bank_mask:0xf bound_ctrl:1
	v_pk_fma_f32 v[16:17], v[20:21], v[114:115], v[16:17] op_sel_hi:[0,1,1]
	v_pk_mul_f32 v[24:25], v[10:11], v[104:105]
	v_add_f32_dpp v18, v18, v18 quad_perm:[2,3,0,1] row_mask:0xf bank_mask:0xf bound_ctrl:1
	v_pk_fma_f32 v[24:25], v[12:13], v[106:107], v[24:25]
	s_waitcnt lgkmcnt(5)
	ds_read_b128 v[88:91], v46 offset:1536
	v_add_f32_dpp v18, v18, v18 row_ror:4 row_mask:0xf bank_mask:0xf bound_ctrl:1
	ds_read_b128 v[100:103], v46 offset:13824
	v_add_f32_e32 v28, v24, v25
	ds_read_b128 v[92:95], v46 offset:5632
	v_add_f32_dpp v18, v18, v18 row_ror:8 row_mask:0xf bank_mask:0xf bound_ctrl:1
	ds_read_b128 v[96:99], v46 offset:9728
	ds_read_b128 v[104:107], v46 offset:17920
	v_pk_fma_f32 v[10:11], v[18:19], v[116:117], v[14:15] op_sel_hi:[0,1,1]
	v_pk_fma_f32 v[12:13], v[18:19], v[118:119], v[16:17] op_sel_hi:[0,1,1]
	v_mov_b32_dpp v20, v42 row_newbcast:4 row_mask:0xf bank_mask:0xf
	v_pk_mul_f32 v[22:23], v[10:11], v[60:61]
	v_pk_fma_f32 v[22:23], v[12:13], v[62:63], v[22:23]
	v_pk_fma_f32 v[14:15], v[10:11], v[48:49], v[10:11]
	v_add_f32_e32 v18, v22, v23
	v_pk_fma_f32 v[16:17], v[12:13], v[50:51], v[12:13]
	v_pk_fma_f32 v[14:15], v[20:21], v[52:53], v[14:15] op_sel_hi:[0,1,1]
	v_add_f32_dpp v18, v18, v18 quad_perm:[1,0,3,2] row_mask:0xf bank_mask:0xf bound_ctrl:1
	v_pk_fma_f32 v[16:17], v[20:21], v[54:55], v[16:17] op_sel_hi:[0,1,1]
	v_pk_mul_f32 v[24:25], v[10:11], v[124:125]
	v_add_f32_dpp v18, v18, v18 quad_perm:[2,3,0,1] row_mask:0xf bank_mask:0xf bound_ctrl:1
	v_pk_fma_f32 v[24:25], v[12:13], v[126:127], v[24:25]
	s_waitcnt lgkmcnt(5)
	ds_read_b128 v[108:111], v46 offset:1792
	v_add_f32_dpp v18, v18, v18 row_ror:4 row_mask:0xf bank_mask:0xf bound_ctrl:1
	ds_read_b128 v[120:123], v46 offset:14080
	v_add_f32_e32 v29, v24, v25
	ds_read_b128 v[112:115], v46 offset:5888
	v_add_f32_dpp v18, v18, v18 row_ror:8 row_mask:0xf bank_mask:0xf bound_ctrl:1
	ds_read_b128 v[116:119], v46 offset:9984
	ds_read_b128 v[124:127], v46 offset:18176
	v_pk_fma_f32 v[10:11], v[18:19], v[56:57], v[14:15] op_sel_hi:[0,1,1]
	v_pk_fma_f32 v[12:13], v[18:19], v[58:59], v[16:17] op_sel_hi:[0,1,1]
	v_mov_b32_dpp v20, v42 row_newbcast:5 row_mask:0xf bank_mask:0xf
	v_pk_mul_f32 v[22:23], v[10:11], v[80:81]
	v_pk_fma_f32 v[22:23], v[12:13], v[82:83], v[22:23]
	v_pk_fma_f32 v[14:15], v[10:11], v[68:69], v[10:11]
	v_add_f32_e32 v18, v22, v23
	v_pk_fma_f32 v[16:17], v[12:13], v[70:71], v[12:13]
	v_pk_fma_f32 v[14:15], v[20:21], v[72:73], v[14:15] op_sel_hi:[0,1,1]
	v_add_f32_dpp v18, v18, v18 quad_perm:[1,0,3,2] row_mask:0xf bank_mask:0xf bound_ctrl:1
	v_pk_fma_f32 v[16:17], v[20:21], v[74:75], v[16:17] op_sel_hi:[0,1,1]
	v_pk_mul_f32 v[24:25], v[10:11], v[64:65]
	v_add_f32_dpp v18, v18, v18 quad_perm:[2,3,0,1] row_mask:0xf bank_mask:0xf bound_ctrl:1
	v_pk_fma_f32 v[24:25], v[12:13], v[66:67], v[24:25]
	s_waitcnt lgkmcnt(5)
	ds_read_b128 v[48:51], v46 offset:2048
	v_add_f32_dpp v18, v18, v18 row_ror:4 row_mask:0xf bank_mask:0xf bound_ctrl:1
	ds_read_b128 v[60:63], v46 offset:14336
	v_add_f32_e32 v30, v24, v25
	ds_read_b128 v[52:55], v46 offset:6144
	v_add_f32_dpp v18, v18, v18 row_ror:8 row_mask:0xf bank_mask:0xf bound_ctrl:1
	ds_read_b128 v[56:59], v46 offset:10240
	ds_read_b128 v[64:67], v46 offset:18432
	v_pk_fma_f32 v[10:11], v[18:19], v[76:77], v[14:15] op_sel_hi:[0,1,1]
	v_pk_fma_f32 v[12:13], v[18:19], v[78:79], v[16:17] op_sel_hi:[0,1,1]
	v_mov_b32_dpp v20, v42 row_newbcast:6 row_mask:0xf bank_mask:0xf
	v_pk_mul_f32 v[22:23], v[10:11], v[100:101]
	v_pk_fma_f32 v[22:23], v[12:13], v[102:103], v[22:23]
	v_pk_fma_f32 v[14:15], v[10:11], v[88:89], v[10:11]
	v_add_f32_e32 v18, v22, v23
	v_pk_fma_f32 v[16:17], v[12:13], v[90:91], v[12:13]
	v_pk_fma_f32 v[14:15], v[20:21], v[92:93], v[14:15] op_sel_hi:[0,1,1]
	v_add_f32_dpp v18, v18, v18 quad_perm:[1,0,3,2] row_mask:0xf bank_mask:0xf bound_ctrl:1
	v_pk_fma_f32 v[16:17], v[20:21], v[94:95], v[16:17] op_sel_hi:[0,1,1]
	v_pk_mul_f32 v[24:25], v[10:11], v[84:85]
	v_add_f32_dpp v18, v18, v18 quad_perm:[2,3,0,1] row_mask:0xf bank_mask:0xf bound_ctrl:1
	v_pk_fma_f32 v[24:25], v[12:13], v[86:87], v[24:25]
	s_waitcnt lgkmcnt(5)
; __device__ __forceinline__ float row_sum16(float v) { v += __shfl_xor(v, 1); v += __shfl_xor(v, 2); v += __shfl_xor(v, 4); v += __shfl_xor(v, 8); return v; }
; __device__ __forceinline__ float row_sum16(float v) { v += dppf<0xB1>(v); v += dppf<0x4E>(v); v += dppf<0x124>(v); v += dppf<0x128>(v); return v; }
; #define RW_LOAD(slot, step) do { const size_t ro_ = (size_t)row_of(step) * RWW; \
;       s_ok[slot] = *(const h16x8*)((p_rec + ro_ * 3) + urec); s_b[slot] = *(const h16x4*)((p_rec + ro_ * 3) + urec + 8); \
;       s_kr[slot] = *(const h16x8*)((p_sh + ro_ * 2) + ush); s_v[slot] = (p_v + ro_)[uvoff]; } while (0)
; template <int VAR>
; __device__ __forceinline__ void ph_rw_scan(const Params& P) {
;     ...
; #pragma unroll
;       for (int uu = 0; uu < RW_U; ++uu) {
;         const float vv = (float)s_v[uu];
;         const u32x4 p_ok = __builtin_bit_cast(u32x4, s_ok[uu]), p_kr = __builtin_bit_cast(u32x4, s_kr[uu]);
;         const u32x2 p_bb = __builtin_bit_cast(u32x2, s_b[uu]);
;         const unsigned om0 = p_ok[0], om1 = p_ok[1], kd0 = p_ok[2], kd1 = p_ok[3];
;         const unsigned kk0 = p_kr[0], kk1 = p_kr[1], r0_ = p_kr[2], r1_ = p_kr[3];
;         const unsigned b0_ = p_bb[0], b1_ = p_bb[1];
;         float sa = fmix_lo(S[0], kk0, 0.f); sa = fmix_hi(S[1], kk0, sa);
;         float sb = fmix_lo(S[2], kk1, 0.f); sb = fmix_hi(S[3], kk1, sb);
;         sa = row_sum16(sa + sb);
;         S[0] = fmix_lo(S[0], om0, S[0]); S[1] = fmix_hi(S[1], om0, S[1]); S[2] = fmix_lo(S[2], om1, S[2]); S[3] = fmix_hi(S[3], om1, S[3]);
;         S[0] = fmix_lo(sa, b0_, S[0]); S[1] = fmix_hi(sa, b0_, S[1]); S[2] = fmix_lo(sa, b1_, S[2]); S[3] = fmix_hi(sa, b1_, S[3]);
;         S[0] = fmix_lo(vv, kd0, S[0]); S[1] = fmix_hi(vv, kd0, S[1]); S[2] = fmix_lo(vv, kd1, S[2]); S[3] = fmix_hi(vv, kd1, S[3]);
;         float y = fmix_lo(S[0], r0_, 0.f); y = fmix_hi(S[1], r0_, y);
;         float y2 = fmix_lo(S[2], r1_, 0.f); y2 = fmix_hi(S[3], r1_, y2);
;         y += y2;
;         if (VAR == 0 && islat) {
;           y = row_sum16(y);
;           if (q == 0) yout[((size_t)dir * NL + row_of(t0 + uu)) * RWW + hh * 64 + vrow] = (h16)y;
;         }
;         if (VAR != 0) asm volatile("" :: "v"(y));
;         const int nstep = t0 + uu + RW_U < RW_NS ? t0 + uu + RW_U : RW_NS - 1;
;         if (VAR != 2) RW_LOAD(uu, nstep);
	ds_read_b128 v[68:71], v46 offset:2304
	v_add_f32_dpp v18, v18, v18 row_ror:4 row_mask:0xf bank_mask:0xf bound_ctrl:1
	ds_read_b128 v[80:83], v46 offset:14592
	v_add_f32_e32 v31, v24, v25
	ds_read_b128 v[72:75], v46 offset:6400
	v_add_f32_dpp v18, v18, v18 row_ror:8 row_mask:0xf bank_mask:0xf bound_ctrl:1
	ds_read_b128 v[76:79], v46 offset:10496
	ds_read_b128 v[84:87], v46 offset:18688
	v_pk_fma_f32 v[10:11], v[18:19], v[96:97], v[14:15] op_sel_hi:[0,1,1]
	v_pk_fma_f32 v[12:13], v[18:19], v[98:99], v[16:17] op_sel_hi:[0,1,1]
	v_mov_b32_dpp v20, v42 row_newbcast:7 row_mask:0xf bank_mask:0xf
	v_pk_mul_f32 v[22:23], v[10:11], v[120:121]
	v_pk_fma_f32 v[22:23], v[12:13], v[122:123], v[22:23]
	v_pk_fma_f32 v[14:15], v[10:11], v[108:109], v[10:11]
	v_add_f32_e32 v18, v22, v23
	v_pk_fma_f32 v[16:17], v[12:13], v[110:111], v[12:13]
	v_pk_fma_f32 v[14:15], v[20:21], v[112:113], v[14:15] op_sel_hi:[0,1,1]
	v_add_f32_dpp v18, v18, v18 quad_perm:[1,0,3,2] row_mask:0xf bank_mask:0xf bound_ctrl:1
	v_pk_fma_f32 v[16:17], v[20:21], v[114:115], v[16:17] op_sel_hi:[0,1,1]
	v_pk_mul_f32 v[24:25], v[10:11], v[104:105]
	v_add_f32_dpp v18, v18, v18 quad_perm:[2,3,0,1] row_mask:0xf bank_mask:0xf bound_ctrl:1
	v_pk_fma_f32 v[24:25], v[12:13], v[106:107], v[24:25]
	s_waitcnt lgkmcnt(5)
	ds_read_b128 v[88:91], v46 offset:2560
	v_add_f32_dpp v18, v18, v18 row_ror:4 row_mask:0xf bank_mask:0xf bound_ctrl:1
	ds_read_b128 v[100:103], v46 offset:14848
	v_add_f32_e32 v32, v24, v25
	ds_read_b128 v[92:95], v46 offset:6656
	v_add_f32_dpp v18, v18, v18 row_ror:8 row_mask:0xf bank_mask:0xf bound_ctrl:1
	ds_read_b128 v[96:99], v46 offset:10752
	ds_read_b128 v[104:107], v46 offset:18944
	v_pk_fma_f32 v[10:11], v[18:19], v[116:117], v[14:15] op_sel_hi:[0,1,1]
	v_pk_fma_f32 v[12:13], v[18:19], v[118:119], v[16:17] op_sel_hi:[0,1,1]
	v_mov_b32_dpp v20, v42 row_newbcast:8 row_mask:0xf bank_mask:0xf
	v_pk_mul_f32 v[22:23], v[10:11], v[60:61]
	v_pk_fma_f32 v[22:23], v[12:13], v[62:63], v[22:23]
	v_pk_fma_f32 v[14:15], v[10:11], v[48:49], v[10:11]
	v_add_f32_e32 v18, v22, v23
	v_pk_fma_f32 v[16:17], v[12:13], v[50:51], v[12:13]
	v_pk_fma_f32 v[14:15], v[20:21], v[52:53], v[14:15] op_sel_hi:[0,1,1]
	v_add_f32_dpp v18, v18, v18 quad_perm:[1,0,3,2] row_mask:0xf bank_mask:0xf bound_ctrl:1
	v_pk_fma_f32 v[16:17], v[20:21], v[54:55], v[16:17] op_sel_hi:[0,1,1]
	v_pk_mul_f32 v[24:25], v[10:11], v[124:125]
	v_add_f32_dpp v18, v18, v18 quad_perm:[2,3,0,1] row_mask:0xf bank_mask:0xf bound_ctrl:1
	v_pk_fma_f32 v[24:25], v[12:13], v[126:127], v[24:25]
	s_waitcnt lgkmcnt(5)
	ds_read_b128 v[108:111], v46 offset:2816
	v_add_f32_dpp v18, v18, v18 row_ror:4 row_mask:0xf bank_mask:0xf bound_ctrl:1
	ds_read_b128 v[120:123], v46 offset:15104
	v_add_f32_e32 v33, v24, v25
	ds_read_b128 v[112:115], v46 offset:6912
	v_add_f32_dpp v18, v18, v18 row_ror:8 row_mask:0xf bank_mask:0xf bound_ctrl:1
	ds_read_b128 v[116:119], v46 offset:11008
	ds_read_b128 v[124:127], v46 offset:19200
	v_pk_fma_f32 v[10:11], v[18:19], v[56:57], v[14:15] op_sel_hi:[0,1,1]
	v_pk_fma_f32 v[12:13], v[18:19], v[58:59], v[16:17] op_sel_hi:[0,1,1]
	v_mov_b32_dpp v20, v42 row_newbcast:9 row_mask:0xf bank_mask:0xf
	v_pk_mul_f32 v[22:23], v[10:11], v[80:81]
	v_pk_fma_f32 v[22:23], v[12:13], v[82:83], v[22:23]
	v_pk_fma_f32 v[14:15], v[10:11], v[68:69], v[10:11]
	v_add_f32_e32 v18, v22, v23
	v_pk_fma_f32 v[16:17], v[12:13], v[70:71], v[12:13]
	v_pk_fma_f32 v[14:15], v[20:21], v[72:73], v[14:15] op_sel_hi:[0,1,1]
	v_add_f32_dpp v18, v18, v18 quad_perm:[1,0,3,2] row_mask:0xf bank_mask:0xf bound_ctrl:1
	v_pk_fma_f32 v[16:17], v[20:21], v[74:75], v[16:17] op_sel_hi:[0,1,1]
	v_pk_mul_f32 v[24:25], v[10:11], v[64:65]
	v_add_f32_dpp v18, v18, v18 quad_perm:[2,3,0,1] row_mask:0xf bank_mask:0xf bound_ctrl:1
	v_pk_fma_f32 v[24:25], v[12:13], v[66:67], v[24:25]
	s_waitcnt lgkmcnt(5)
	ds_read_b128 v[48:51], v46 offset:3072
	v_add_f32_dpp v18, v18, v18 row_ror:4 row_mask:0xf bank_mask:0xf bound_ctrl:1
	ds_read_b128 v[60:63], v46 offset:15360
	v_add_f32_e32 v34, v24, v25
	ds_read_b128 v[52:55], v46 offset:7168
	v_add_f32_dpp v18, v18, v18 row_ror:8 row_mask:0xf bank_mask:0xf bound_ctrl:1
	ds_read_b128 v[56:59], v46 offset:11264
	ds_read_b128 v[64:67], v46 offset:19456
	v_pk_fma_f32 v[10:11], v[18:19], v[76:77], v[14:15] op_sel_hi:[0,1,1]
	v_pk_fma_f32 v[12:13], v[18:19], v[78:79], v[16:17] op_sel_hi:[0,1,1]
	v_mov_b32_dpp v20, v42 row_newbcast:10 row_mask:0xf bank_mask:0xf
	v_pk_mul_f32 v[22:23], v[10:11], v[100:101]
	v_pk_fma_f32 v[22:23], v[12:13], v[102:103], v[22:23]
	v_pk_fma_f32 v[14:15], v[10:11], v[88:89], v[10:11]
	v_add_f32_e32 v18, v22, v23
	v_pk_fma_f32 v[16:17], v[12:13], v[90:91], v[12:13]
	v_pk_fma_f32 v[14:15], v[20:21], v[92:93], v[14:15] op_sel_hi:[0,1,1]
	v_add_f32_dpp v18, v18, v18 quad_perm:[1,0,3,2] row_mask:0xf bank_mask:0xf bound_ctrl:1
	v_pk_fma_f32 v[16:17], v[20:21], v[94:95], v[16:17] op_sel_hi:[0,1,1]
	v_pk_mul_f32 v[24:25], v[10:11], v[84:85]
	v_add_f32_dpp v18, v18, v18 quad_perm:[2,3,0,1] row_mask:0xf bank_mask:0xf bound_ctrl:1
	v_pk_fma_f32 v[24:25], v[12:13], v[86:87], v[24:25]
	s_waitcnt lgkmcnt(5)
; __device__ __forceinline__ float row_sum16(float v) { v += __shfl_xor(v, 1); v += __shfl_xor(v, 2); v += __shfl_xor(v, 4); v += __shfl_xor(v, 8); return v; }
; __device__ __forceinline__ float row_sum16(float v) { v += dppf<0xB1>(v); v += dppf<0x4E>(v); v += dppf<0x124>(v); v += dppf<0x128>(v); return v; }
; #define RW_LOAD(slot, step) do { const size_t ro_ = (size_t)row_of(step) * RWW; \
;       s_ok[slot] = *(const h16x8*)((p_rec + ro_ * 3) + urec); s_b[slot] = *(const h16x4*)((p_rec + ro_ * 3) + urec + 8); \
;       s_kr[slot] = *(const h16x8*)((p_sh + ro_ * 2) + ush); s_v[slot] = (p_v + ro_)[uvoff]; } while (0)
; template <int VAR>
; __device__ __forceinline__ void ph_rw_scan(const Params& P) {
;     ...
; #pragma unroll
;       for (int uu = 0; uu < RW_U; ++uu) {
;         const float vv = (float)s_v[uu];
;         const u32x4 p_ok = __builtin_bit_cast(u32x4, s_ok[uu]), p_kr = __builtin_bit_cast(u32x4, s_kr[uu]);
;         const u32x2 p_bb = __builtin_bit_cast(u32x2, s_b[uu]);
;         const unsigned om0 = p_ok[0], om1 = p_ok[1], kd0 = p_ok[2], kd1 = p_ok[3];
;         const unsigned kk0 = p_kr[0], kk1 = p_kr[1], r0_ = p_kr[2], r1_ = p_kr[3];
;         const unsigned b0_ = p_bb[0], b1_ = p_bb[1];
;         float sa = fmix_lo(S[0], kk0, 0.f); sa = fmix_hi(S[1], kk0, sa);
;         float sb = fmix_lo(S[2], kk1, 0.f); sb = fmix_hi(S[3], kk1, sb);
;         sa = row_sum16(sa + sb);
;         S[0] = fmix_lo(S[0], om0, S[0]); S[1] = fmix_hi(S[1], om0, S[1]); S[2] = fmix_lo(S[2], om1, S[2]); S[3] = fmix_hi(S[3], om1, S[3]);
;         S[0] = fmix_lo(sa, b0_, S[0]); S[1] = fmix_hi(sa, b0_, S[1]); S[2] = fmix_lo(sa, b1_, S[2]); S[3] = fmix_hi(sa, b1_, S[3]);
;         S[0] = fmix_lo(vv, kd0, S[0]); S[1] = fmix_hi(vv, kd0, S[1]); S[2] = fmix_lo(vv, kd1, S[2]); S[3] = fmix_hi(vv, kd1, S[3]);
;         float y = fmix_lo(S[0], r0_, 0.f); y = fmix_hi(S[1], r0_, y);
;         float y2 = fmix_lo(S[2], r1_, 0.f); y2 = fmix_hi(S[3], r1_, y2);
;         y += y2;
;         if (VAR == 0 && islat) {
;           y = row_sum16(y);
;           if (q == 0) yout[((size_t)dir * NL + row_of(t0 + uu)) * RWW + hh * 64 + vrow] = (h16)y;
;         }
;         if (VAR != 0) asm volatile("" :: "v"(y));
;         const int nstep = t0 + uu + RW_U < RW_NS ? t0 + uu + RW_U : RW_NS - 1;
;         if (VAR != 2) RW_LOAD(uu, nstep);
	ds_read_b128 v[68:71], v46 offset:3328
	v_add_f32_dpp v18, v18, v18 row_ror:4 row_mask:0xf bank_mask:0xf bound_ctrl:1
	ds_read_b128 v[80:83], v46 offset:15616
	v_add_f32_e32 v35, v24, v25
	ds_read_b128 v[72:75], v46 offset:7424
	v_add_f32_dpp v18, v18, v18 row_ror:8 row_mask:0xf bank_mask:0xf bound_ctrl:1
	ds_read_b128 v[76:79], v46 offset:11520
	ds_read_b128 v[84:87], v46 offset:19712
	v_pk_fma_f32 v[10:11], v[18:19], v[96:97], v[14:15] op_sel_hi:[0,1,1]
	v_pk_fma_f32 v[12:13], v[18:19], v[98:99], v[16:17] op_sel_hi:[0,1,1]
	v_mov_b32_dpp v20, v42 row_newbcast:11 row_mask:0xf bank_mask:0xf
	v_pk_mul_f32 v[22:23], v[10:11], v[120:121]
	v_pk_fma_f32 v[22:23], v[12:13], v[122:123], v[22:23]
	v_pk_fma_f32 v[14:15], v[10:11], v[108:109], v[10:11]
	v_add_f32_e32 v18, v22, v23
	v_pk_fma_f32 v[16:17], v[12:13], v[110:111], v[12:13]
	v_pk_fma_f32 v[14:15], v[20:21], v[112:113], v[14:15] op_sel_hi:[0,1,1]
	v_add_f32_dpp v18, v18, v18 quad_perm:[1,0,3,2] row_mask:0xf bank_mask:0xf bound_ctrl:1
	v_pk_fma_f32 v[16:17], v[20:21], v[114:115], v[16:17] op_sel_hi:[0,1,1]
	v_pk_mul_f32 v[24:25], v[10:11], v[104:105]
	v_add_f32_dpp v18, v18, v18 quad_perm:[2,3,0,1] row_mask:0xf bank_mask:0xf bound_ctrl:1
	v_pk_fma_f32 v[24:25], v[12:13], v[106:107], v[24:25]
	s_waitcnt lgkmcnt(5)
	ds_read_b128 v[88:91], v46 offset:3584
	v_add_f32_dpp v18, v18, v18 row_ror:4 row_mask:0xf bank_mask:0xf bound_ctrl:1
	ds_read_b128 v[100:103], v46 offset:15872
	v_add_f32_e32 v36, v24, v25
	ds_read_b128 v[92:95], v46 offset:7680
	v_add_f32_dpp v18, v18, v18 row_ror:8 row_mask:0xf bank_mask:0xf bound_ctrl:1
	ds_read_b128 v[96:99], v46 offset:11776
	ds_read_b128 v[104:107], v46 offset:19968
	v_pk_fma_f32 v[10:11], v[18:19], v[116:117], v[14:15] op_sel_hi:[0,1,1]
	v_pk_fma_f32 v[12:13], v[18:19], v[118:119], v[16:17] op_sel_hi:[0,1,1]
	v_mov_b32_dpp v20, v42 row_newbcast:12 row_mask:0xf bank_mask:0xf
	v_pk_mul_f32 v[22:23], v[10:11], v[60:61]
	v_pk_fma_f32 v[22:23], v[12:13], v[62:63], v[22:23]
	v_pk_fma_f32 v[14:15], v[10:11], v[48:49], v[10:11]
	v_add_f32_e32 v18, v22, v23
	v_pk_fma_f32 v[16:17], v[12:13], v[50:51], v[12:13]
	v_pk_fma_f32 v[14:15], v[20:21], v[52:53], v[14:15] op_sel_hi:[0,1,1]
	v_add_f32_dpp v18, v18, v18 quad_perm:[1,0,3,2] row_mask:0xf bank_mask:0xf bound_ctrl:1
	v_pk_fma_f32 v[16:17], v[20:21], v[54:55], v[16:17] op_sel_hi:[0,1,1]
	v_pk_mul_f32 v[24:25], v[10:11], v[124:125]
	v_add_f32_dpp v18, v18, v18 quad_perm:[2,3,0,1] row_mask:0xf bank_mask:0xf bound_ctrl:1
	v_pk_fma_f32 v[24:25], v[12:13], v[126:127], v[24:25]
	s_waitcnt lgkmcnt(5)
	ds_read_b128 v[108:111], v46 offset:3840
	v_add_f32_dpp v18, v18, v18 row_ror:4 row_mask:0xf bank_mask:0xf bound_ctrl:1
	ds_read_b128 v[120:123], v46 offset:16128
	v_add_f32_e32 v37, v24, v25
	ds_read_b128 v[112:115], v46 offset:7936
	v_add_f32_dpp v18, v18, v18 row_ror:8 row_mask:0xf bank_mask:0xf bound_ctrl:1
	ds_read_b128 v[116:119], v46 offset:12032
	ds_read_b128 v[124:127], v46 offset:20224
	v_pk_fma_f32 v[10:11], v[18:19], v[56:57], v[14:15] op_sel_hi:[0,1,1]
	v_pk_fma_f32 v[12:13], v[18:19], v[58:59], v[16:17] op_sel_hi:[0,1,1]
	v_mov_b32_dpp v20, v42 row_newbcast:13 row_mask:0xf bank_mask:0xf
	v_pk_mul_f32 v[22:23], v[10:11], v[80:81]
	v_pk_fma_f32 v[22:23], v[12:13], v[82:83], v[22:23]
	v_pk_fma_f32 v[14:15], v[10:11], v[68:69], v[10:11]
	v_add_f32_e32 v18, v22, v23
	v_pk_fma_f32 v[16:17], v[12:13], v[70:71], v[12:13]
	v_pk_fma_f32 v[14:15], v[20:21], v[72:73], v[14:15] op_sel_hi:[0,1,1]
	v_add_f32_dpp v18, v18, v18 quad_perm:[1,0,3,2] row_mask:0xf bank_mask:0xf bound_ctrl:1
	v_pk_fma_f32 v[16:17], v[20:21], v[74:75], v[16:17] op_sel_hi:[0,1,1]
	v_pk_mul_f32 v[24:25], v[10:11], v[64:65]
	v_add_f32_dpp v18, v18, v18 quad_perm:[2,3,0,1] row_mask:0xf bank_mask:0xf bound_ctrl:1
	v_pk_fma_f32 v[24:25], v[12:13], v[66:67], v[24:25]
	s_waitcnt lgkmcnt(5)
	ds_read_b128 v[48:51], v47
	v_add_f32_dpp v18, v18, v18 row_ror:4 row_mask:0xf bank_mask:0xf bound_ctrl:1
	ds_read_b128 v[60:63], v47 offset:12288
	v_add_f32_e32 v38, v24, v25
	ds_read_b128 v[52:55], v47 offset:4096
	v_add_f32_dpp v18, v18, v18 row_ror:8 row_mask:0xf bank_mask:0xf bound_ctrl:1
	ds_read_b128 v[56:59], v47 offset:8192
	ds_read_b128 v[64:67], v47 offset:16384
	v_pk_fma_f32 v[10:11], v[18:19], v[76:77], v[14:15] op_sel_hi:[0,1,1]
	v_pk_fma_f32 v[12:13], v[18:19], v[78:79], v[16:17] op_sel_hi:[0,1,1]
	v_mov_b32_dpp v20, v42 row_newbcast:14 row_mask:0xf bank_mask:0xf
	v_pk_mul_f32 v[22:23], v[10:11], v[100:101]
	v_pk_fma_f32 v[22:23], v[12:13], v[102:103], v[22:23]
	v_pk_fma_f32 v[14:15], v[10:11], v[88:89], v[10:11]
	v_add_f32_e32 v18, v22, v23
	v_pk_fma_f32 v[16:17], v[12:13], v[90:91], v[12:13]
	v_pk_fma_f32 v[14:15], v[20:21], v[92:93], v[14:15] op_sel_hi:[0,1,1]
	v_add_f32_dpp v18, v18, v18 quad_perm:[1,0,3,2] row_mask:0xf bank_mask:0xf bound_ctrl:1
	v_pk_fma_f32 v[16:17], v[20:21], v[94:95], v[16:17] op_sel_hi:[0,1,1]
	v_pk_mul_f32 v[24:25], v[10:11], v[84:85]
	v_add_f32_dpp v18, v18, v18 quad_perm:[2,3,0,1] row_mask:0xf bank_mask:0xf bound_ctrl:1
	v_pk_fma_f32 v[24:25], v[12:13], v[86:87], v[24:25]
	s_waitcnt lgkmcnt(5)
; __device__ __forceinline__ float row_sum16(float v) { v += __shfl_xor(v, 1); v += __shfl_xor(v, 2); v += __shfl_xor(v, 4); v += __shfl_xor(v, 8); return v; }
; __device__ __forceinline__ float row_sum16(float v) { v += dppf<0xB1>(v); v += dppf<0x4E>(v); v += dppf<0x124>(v); v += dppf<0x128>(v); return v; }
; template <int VAR>
; __device__ __forceinline__ void ph_rw_scan(const Params& P) {
;     ...
;     for (int t0 = 0; t0 < RW_NS; t0 += RW_U) {
;       const bool islat = t0 >= CTX_LEN;
; #pragma unroll
;       for (int uu = 0; uu < RW_U; ++uu) {
;         const float vv = (float)s_v[uu];
;         const u32x4 p_ok = __builtin_bit_cast(u32x4, s_ok[uu]), p_kr = __builtin_bit_cast(u32x4, s_kr[uu]);
;         const u32x2 p_bb = __builtin_bit_cast(u32x2, s_b[uu]);
;         const unsigned om0 = p_ok[0], om1 = p_ok[1], kd0 = p_ok[2], kd1 = p_ok[3];
;         const unsigned kk0 = p_kr[0], kk1 = p_kr[1], r0_ = p_kr[2], r1_ = p_kr[3];
;         const unsigned b0_ = p_bb[0], b1_ = p_bb[1];
;         float sa = fmix_lo(S[0], kk0, 0.f); sa = fmix_hi(S[1], kk0, sa);
;         float sb = fmix_lo(S[2], kk1, 0.f); sb = fmix_hi(S[3], kk1, sb);
;         sa = row_sum16(sa + sb);
;         S[0] = fmix_lo(S[0], om0, S[0]); S[1] = fmix_hi(S[1], om0, S[1]); S[2] = fmix_lo(S[2], om1, S[2]); S[3] = fmix_hi(S[3], om1, S[3]);
;         S[0] = fmix_lo(sa, b0_, S[0]); S[1] = fmix_hi(sa, b0_, S[1]); S[2] = fmix_lo(sa, b1_, S[2]); S[3] = fmix_hi(sa, b1_, S[3]);
;         S[0] = fmix_lo(vv, kd0, S[0]); S[1] = fmix_hi(vv, kd0, S[1]); S[2] = fmix_lo(vv, kd1, S[2]); S[3] = fmix_hi(vv, kd1, S[3]);
;         float y = fmix_lo(S[0], r0_, 0.f); y = fmix_hi(S[1], r0_, y);
;         float y2 = fmix_lo(S[2], r1_, 0.f); y2 = fmix_hi(S[3], r1_, y2);
;         y += y2;
;         if (VAR == 0 && islat) {
;           y = row_sum16(y);
;           if (q == 0) yout[((size_t)dir * NL + row_of(t0 + uu)) * RWW + hh * 64 + vrow] = (h16)y;
;         }
;         if (VAR != 0) asm volatile("" :: "v"(y));
;         const int nstep = t0 + uu + RW_U < RW_NS ? t0 + uu + RW_U : RW_NS - 1;
;         if (VAR != 2) RW_LOAD(uu, nstep);
	ds_read_b128 v[68:71], v47 offset:256
	v_add_f32_dpp v18, v18, v18 row_ror:4 row_mask:0xf bank_mask:0xf bound_ctrl:1
	ds_read_b128 v[80:83], v47 offset:12544
	v_add_f32_e32 v39, v24, v25
	ds_read_b128 v[72:75], v47 offset:4352
	v_add_f32_dpp v18, v18, v18 row_ror:8 row_mask:0xf bank_mask:0xf bound_ctrl:1
	ds_read_b128 v[76:79], v47 offset:8448
	ds_read_b128 v[84:87], v47 offset:16640
	v_pk_fma_f32 v[10:11], v[18:19], v[96:97], v[14:15] op_sel_hi:[0,1,1]
	v_pk_fma_f32 v[12:13], v[18:19], v[98:99], v[16:17] op_sel_hi:[0,1,1]
	v_mov_b32_dpp v20, v42 row_newbcast:15 row_mask:0xf bank_mask:0xf
	v_pk_mul_f32 v[22:23], v[10:11], v[120:121]
	v_pk_fma_f32 v[22:23], v[12:13], v[122:123], v[22:23]
	v_pk_fma_f32 v[14:15], v[10:11], v[108:109], v[10:11]
	v_add_f32_e32 v18, v22, v23
	v_pk_fma_f32 v[16:17], v[12:13], v[110:111], v[12:13]
	v_pk_fma_f32 v[14:15], v[20:21], v[112:113], v[14:15] op_sel_hi:[0,1,1]
	v_add_f32_dpp v18, v18, v18 quad_perm:[1,0,3,2] row_mask:0xf bank_mask:0xf bound_ctrl:1
	v_pk_fma_f32 v[16:17], v[20:21], v[114:115], v[16:17] op_sel_hi:[0,1,1]
	v_pk_mul_f32 v[24:25], v[10:11], v[104:105]
	v_add_f32_dpp v18, v18, v18 quad_perm:[2,3,0,1] row_mask:0xf bank_mask:0xf bound_ctrl:1
	v_pk_fma_f32 v[24:25], v[12:13], v[106:107], v[24:25]
	s_waitcnt lgkmcnt(5)
	ds_read_b128 v[88:91], v47 offset:512
	v_add_f32_dpp v18, v18, v18 row_ror:4 row_mask:0xf bank_mask:0xf bound_ctrl:1
	ds_read_b128 v[100:103], v47 offset:12800
	v_add_f32_e32 v40, v24, v25
	ds_read_b128 v[92:95], v47 offset:4608
	v_add_f32_dpp v18, v18, v18 row_ror:8 row_mask:0xf bank_mask:0xf bound_ctrl:1
	ds_read_b128 v[96:99], v47 offset:8704
	ds_read_b128 v[104:107], v47 offset:16896
	v_pk_fma_f32 v[10:11], v[18:19], v[116:117], v[14:15] op_sel_hi:[0,1,1]
	v_pk_fma_f32 v[12:13], v[18:19], v[118:119], v[16:17] op_sel_hi:[0,1,1]
	s_waitcnt vmcnt(0)
	v_cvt_f32_f16_e32 v42, v43
	s_mov_b32 s26, s27
	s_add_u32 s27, s27, 20480
	s_cmp_eq_u32 s27, 61440
	s_cselect_b32 s27, 0, s27
	v_add_u32_e32 v46, s26, v8
	v_add_u32_e32 v47, s27, v8
	s_barrier
	s_add_u32 s3, s3, 1
	s_cmp_lt_u32 s3, 0x410
	s_cbranch_scc1 .Lscan_loop_d1
	v_pk_mul_f32 v[24:25], v[10:11], v[124:125]
	v_pk_fma_f32 v[24:25], v[12:13], v[126:127], v[24:25]
	v_add_f32_e32 v41, v24, v25
	s_nop 1
	v_add_f32_dpp v26, v26, v26 row_ror:8 row_mask:0xf bank_mask:0xf bound_ctrl:1
	v_add_f32_dpp v27, v27, v27 row_ror:8 row_mask:0xf bank_mask:0xf bound_ctrl:1
	v_add_f32_dpp v28, v28, v28 row_ror:8 row_mask:0xf bank_mask:0xf bound_ctrl:1
	v_add_f32_dpp v29, v29, v29 row_ror:8 row_mask:0xf bank_mask:0xf bound_ctrl:1
	v_add_f32_dpp v30, v30, v30 row_ror:8 row_mask:0xf bank_mask:0xf bound_ctrl:1
	v_add_f32_dpp v31, v31, v31 row_ror:8 row_mask:0xf bank_mask:0xf bound_ctrl:1
	v_add_f32_dpp v32, v32, v32 row_ror:8 row_mask:0xf bank_mask:0xf bound_ctrl:1
	v_add_f32_dpp v33, v33, v33 row_ror:8 row_mask:0xf bank_mask:0xf bound_ctrl:1
	v_add_f32_dpp v26, v34, v34 row_ror:8 row_mask:0xf bank_mask:0xc bound_ctrl:1
	v_add_f32_dpp v27, v35, v35 row_ror:8 row_mask:0xf bank_mask:0xc bound_ctrl:1
	v_add_f32_dpp v28, v36, v36 row_ror:8 row_mask:0xf bank_mask:0xc bound_ctrl:1
	v_add_f32_dpp v29, v37, v37 row_ror:8 row_mask:0xf bank_mask:0xc bound_ctrl:1
	v_add_f32_dpp v30, v38, v38 row_ror:8 row_mask:0xf bank_mask:0xc bound_ctrl:1
	v_add_f32_dpp v31, v39, v39 row_ror:8 row_mask:0xf bank_mask:0xc bound_ctrl:1
	v_add_f32_dpp v32, v40, v40 row_ror:8 row_mask:0xf bank_mask:0xc bound_ctrl:1
	v_add_f32_dpp v33, v41, v41 row_ror:8 row_mask:0xf bank_mask:0xc bound_ctrl:1
	v_add_f32_dpp v26, v26, v26 row_half_mirror row_mask:0xf bank_mask:0xf bound_ctrl:1
	v_add_f32_dpp v27, v27, v27 row_half_mirror row_mask:0xf bank_mask:0xf bound_ctrl:1
	v_add_f32_dpp v28, v28, v28 row_half_mirror row_mask:0xf bank_mask:0xf bound_ctrl:1
	v_add_f32_dpp v29, v29, v29 row_half_mirror row_mask:0xf bank_mask:0xf bound_ctrl:1
	v_add_f32_dpp v26, v30, v30 row_half_mirror row_mask:0xf bank_mask:0xa bound_ctrl:1
	v_add_f32_dpp v27, v31, v31 row_half_mirror row_mask:0xf bank_mask:0xa bound_ctrl:1
	v_add_f32_dpp v28, v32, v32 row_half_mirror row_mask:0xf bank_mask:0xa bound_ctrl:1
	v_add_f32_dpp v29, v33, v33 row_half_mirror row_mask:0xf bank_mask:0xa bound_ctrl:1
	v_add_f32_dpp v26, v26, v26 quad_perm:[1,0,3,2] row_mask:0xf bank_mask:0xf bound_ctrl:1
	v_add_f32_dpp v27, v27, v27 quad_perm:[1,0,3,2] row_mask:0xf bank_mask:0xf bound_ctrl:1
	v_add_f32_dpp v28, v28, v28 quad_perm:[1,0,3,2] row_mask:0xf bank_mask:0xf bound_ctrl:1
	v_add_f32_dpp v29, v29, v29 quad_perm:[1,0,3,2] row_mask:0xf bank_mask:0xf bound_ctrl:1
	v_add_f32_dpp v26, v26, v26 quad_perm:[2,3,0,1] row_mask:0xf bank_mask:0xf bound_ctrl:1
	v_add_f32_dpp v27, v27, v27 quad_perm:[2,3,0,1] row_mask:0xf bank_mask:0xf bound_ctrl:1
	v_add_f32_dpp v28, v28, v28 quad_perm:[2,3,0,1] row_mask:0xf bank_mask:0xf bound_ctrl:1
	v_add_f32_dpp v29, v29, v29 quad_perm:[2,3,0,1] row_mask:0xf bank_mask:0xf bound_ctrl:1
	v_cndmask_b32_e64 v26, v26, v27, s[20:21]
	v_cndmask_b32_e64 v26, v26, v28, s[22:23]
	v_cndmask_b32_e64 v26, v26, v29, s[24:25]
	v_cvt_f16_f32_e32 v45, v26
	global_store_short v44, v45, s[12:13]
	s_sub_u32 s12, s12, 0x8000
	s_subb_u32 s13, s13, 0
	s_waitcnt vmcnt(0) lgkmcnt(0)
	s_branch .Lscan_next
.Lscan_follow:
	s_and_b32 s1, s1, 3
	s_cmp_lg_u32 s29, 0
	s_cbranch_scc1 .Lscan_fdir1
	s_lshl_b32 s30, s1, 2
	v_add_u32_e32 v9, s30, v3
	v_mul_u32_u24_e32 v10, 0x1800, v9
	v_add_u32_e32 v10, v10, v5
	v_lshlrev_b32_e32 v11, 12, v9
	v_add_u32_e32 v11, v11, v6
	s_lshl_b32 s30, s28, 8
	s_add_u32 s30, s30, 0x8000
	s_lshl_b32 s31, s28, 14
	s_mul_i32 s3, s30, 0x1800
	s_add_u32 s6, s4, s3
	s_addc_u32 s7, s5, 0
	s_add_u32 s6, s6, 0x23614000
	s_addc_u32 s7, s7, 0
	s_mul_i32 s3, s30, 0x1000
	s_add_u32 s8, s4, s3
	s_addc_u32 s9, s5, 0
	s_add_u32 s8, s8, 0xbe4c000
	s_addc_u32 s9, s9, 0
	s_mul_i32 s3, s31, 0x1800
	s_add_u32 s14, s4, s3
	s_addc_u32 s15, s5, 0
	s_add_u32 s14, s14, 0x23614000
	s_addc_u32 s15, s15, 0
	s_mul_i32 s3, s31, 0x1000
	s_add_u32 s16, s4, s3
	s_addc_u32 s17, s5, 0
	s_add_u32 s16, s16, 0xbe4c000
	s_addc_u32 s17, s17, 0
	s_mov_b32 s29, 0
	v_add_u32_e32 v13, 0, v12
	global_load_dwordx4 v[16:19], v10, s[6:7]
	global_load_dwordx2 v[20:21], v10, s[6:7] offset:16
	global_load_dwordx4 v[24:27], v11, s[8:9]
	s_add_u32 s29, s29, 1
	s_cmp_eq_u32 s29, 16
	s_cbranch_scc1 .Lscan_stsw_p0_f0
	s_add_u32 s6, s6, 0x18000
	s_addc_u32 s7, s7, 0
	s_add_u32 s8, s8, 0x10000
	s_addc_u32 s9, s9, 0
	s_branch .Lscan_stdone_p0_f0

.Lscan_stdone_p0_f0:
	s_waitcnt vmcnt(0)
	v_cvt_f32_f16_e32 v32, v16
	v_cvt_f32_f16_sdwa v33, v16 dst_sel:DWORD dst_unused:UNUSED_PAD src0_sel:WORD_1
	v_cvt_f32_f16_e32 v34, v17
	v_cvt_f32_f16_sdwa v35, v17 dst_sel:DWORD dst_unused:UNUSED_PAD src0_sel:WORD_1
	v_cvt_f32_f16_e32 v36, v18
	v_cvt_f32_f16_sdwa v37, v18 dst_sel:DWORD dst_unused:UNUSED_PAD src0_sel:WORD_1
	v_cvt_f32_f16_e32 v38, v19
	v_cvt_f32_f16_sdwa v39, v19 dst_sel:DWORD dst_unused:UNUSED_PAD src0_sel:WORD_1
	v_cvt_f32_f16_e32 v40, v20
	v_cvt_f32_f16_sdwa v41, v20 dst_sel:DWORD dst_unused:UNUSED_PAD src0_sel:WORD_1
	v_cvt_f32_f16_e32 v42, v21
	v_cvt_f32_f16_sdwa v43, v21 dst_sel:DWORD dst_unused:UNUSED_PAD src0_sel:WORD_1
	v_cvt_f32_f16_e32 v44, v24
	v_cvt_f32_f16_sdwa v45, v24 dst_sel:DWORD dst_unused:UNUSED_PAD src0_sel:WORD_1
	v_cvt_f32_f16_e32 v46, v25
	v_cvt_f32_f16_sdwa v47, v25 dst_sel:DWORD dst_unused:UNUSED_PAD src0_sel:WORD_1
	v_cvt_f32_f16_e32 v48, v26
	v_cvt_f32_f16_sdwa v49, v26 dst_sel:DWORD dst_unused:UNUSED_PAD src0_sel:WORD_1
	v_cvt_f32_f16_e32 v50, v27
	v_cvt_f32_f16_sdwa v51, v27 dst_sel:DWORD dst_unused:UNUSED_PAD src0_sel:WORD_1
	ds_write_b128 v13, v[32:35]
	ds_write_b128 v13, v[36:39] offset:4096
	ds_write_b128 v13, v[40:43] offset:8192
	ds_write_b128 v13, v[44:47] offset:12288
	ds_write_b128 v13, v[48:51] offset:16384
	v_add_u32_e32 v13, 20480, v12
	global_load_dwordx4 v[16:19], v10, s[6:7]
	global_load_dwordx2 v[20:21], v10, s[6:7] offset:16
	global_load_dwordx4 v[24:27], v11, s[8:9]
	s_add_u32 s29, s29, 1
	s_cmp_eq_u32 s29, 16
	s_cbranch_scc1 .Lscan_stsw_p1_f0
	s_add_u32 s6, s6, 0x18000
	s_addc_u32 s7, s7, 0
	s_add_u32 s8, s8, 0x10000
	s_addc_u32 s9, s9, 0
	s_branch .Lscan_stdone_p1_f0

.Lscan_stdone_p1_f0:
	s_waitcnt vmcnt(0)
	v_cvt_f32_f16_e32 v32, v16
	v_cvt_f32_f16_sdwa v33, v16 dst_sel:DWORD dst_unused:UNUSED_PAD src0_sel:WORD_1
	v_cvt_f32_f16_e32 v34, v17
	v_cvt_f32_f16_sdwa v35, v17 dst_sel:DWORD dst_unused:UNUSED_PAD src0_sel:WORD_1
	v_cvt_f32_f16_e32 v36, v18
	v_cvt_f32_f16_sdwa v37, v18 dst_sel:DWORD dst_unused:UNUSED_PAD src0_sel:WORD_1
	v_cvt_f32_f16_e32 v38, v19
	v_cvt_f32_f16_sdwa v39, v19 dst_sel:DWORD dst_unused:UNUSED_PAD src0_sel:WORD_1
	v_cvt_f32_f16_e32 v40, v20
	v_cvt_f32_f16_sdwa v41, v20 dst_sel:DWORD dst_unused:UNUSED_PAD src0_sel:WORD_1
	v_cvt_f32_f16_e32 v42, v21
	v_cvt_f32_f16_sdwa v43, v21 dst_sel:DWORD dst_unused:UNUSED_PAD src0_sel:WORD_1
	v_cvt_f32_f16_e32 v44, v24
	v_cvt_f32_f16_sdwa v45, v24 dst_sel:DWORD dst_unused:UNUSED_PAD src0_sel:WORD_1
	v_cvt_f32_f16_e32 v46, v25
	v_cvt_f32_f16_sdwa v47, v25 dst_sel:DWORD dst_unused:UNUSED_PAD src0_sel:WORD_1
	v_cvt_f32_f16_e32 v48, v26
	v_cvt_f32_f16_sdwa v49, v26 dst_sel:DWORD dst_unused:UNUSED_PAD src0_sel:WORD_1
	v_cvt_f32_f16_e32 v50, v27
	v_cvt_f32_f16_sdwa v51, v27 dst_sel:DWORD dst_unused:UNUSED_PAD src0_sel:WORD_1
	ds_write_b128 v13, v[32:35]
	ds_write_b128 v13, v[36:39] offset:4096
	ds_write_b128 v13, v[40:43] offset:8192
	ds_write_b128 v13, v[44:47] offset:12288
	ds_write_b128 v13, v[48:51] offset:16384
	global_load_dwordx4 v[16:19], v10, s[6:7]
	global_load_dwordx2 v[20:21], v10, s[6:7] offset:16
	global_load_dwordx4 v[24:27], v11, s[8:9]
	s_add_u32 s29, s29, 1
	s_cmp_eq_u32 s29, 16
	s_cbranch_scc1 .Lscan_stsw_p2_f0
	s_add_u32 s6, s6, 0x18000
	s_addc_u32 s7, s7, 0
	s_add_u32 s8, s8, 0x10000
	s_addc_u32 s9, s9, 0
	s_branch .Lscan_stdone_p2_f0

; #define RW_LOAD(slot, step) do { const size_t ro_ = (size_t)row_of(step) * RWW; \
;       s_ok[slot] = *(const h16x8*)((p_rec + ro_ * 3) + urec); s_b[slot] = *(const h16x4*)((p_rec + ro_ * 3) + urec + 8); \
;       s_kr[slot] = *(const h16x8*)((p_sh + ro_ * 2) + ush); s_v[slot] = (p_v + ro_)[uvoff]; } while (0)
; template <int VAR>
; __device__ __forceinline__ void ph_rw_scan(const Params& P) {
;     ...
; #pragma unroll
;     for (int uu = 0; uu < RW_U; ++uu) RW_LOAD(uu, uu);
;     float S[4] = {0.f, 0.f, 0.f, 0.f};
;     for (int t0 = 0; t0 < RW_NS; t0 += RW_U) {
.Lscan_stdone_p2_f0:
	s_mov_b32 s28, 40960
	v_add_u32_e32 v13, s28, v12
	s_waitcnt lgkmcnt(0)
	s_barrier
	s_mov_b32 s3, 0

; #define RW_LOAD(slot, step) do { const size_t ro_ = (size_t)row_of(step) * RWW; \
;       s_ok[slot] = *(const h16x8*)((p_rec + ro_ * 3) + urec); s_b[slot] = *(const h16x4*)((p_rec + ro_ * 3) + urec + 8); \
;       s_kr[slot] = *(const h16x8*)((p_sh + ro_ * 2) + ush); s_v[slot] = (p_v + ro_)[uvoff]; } while (0)
; template <int VAR>
; __device__ __forceinline__ void ph_rw_scan(const Params& P) {
;     ...
;     auto row_of = [&](int step) -> int {
;       if (step < CTX_LEN) return NL + b * CTX_LEN + (dir == 0 ? step : CTX_LEN - 1 - step);
;       const int s = step - CTX_LEN; return b * SEQ + (dir == 0 ? s : SEQ - 1 - s);
;     };
;     ...
; #pragma unroll
;     for (int uu = 0; uu < RW_U; ++uu) RW_LOAD(uu, uu);
.Lscan_stdone_lp_f0:
	s_add_u32 s28, s28, 20480
	s_cmp_eq_u32 s28, 61440
	s_cselect_b32 s28, 0, s28
	v_add_u32_e32 v13, s28, v12
	s_waitcnt lgkmcnt(0)
	s_barrier
	s_add_u32 s3, s3, 1
	s_cmp_lt_u32 s3, 0x410
	s_cbranch_scc1 .Lscan_floop_f0
	s_waitcnt vmcnt(0)
	s_branch .Lscan_next
.Lscan_fdir1:
	s_lshl_b32 s30, s1, 2
	v_add_u32_e32 v9, s30, v3
	v_sub_u32_e32 v9, 15, v9
	v_mul_u32_u24_e32 v10, 0x1800, v9
	v_add_u32_e32 v10, v10, v5
	v_lshlrev_b32_e32 v11, 12, v9
	v_add_u32_e32 v11, v11, v6
	s_lshl_b32 s30, s28, 8
	s_add_u32 s30, s30, 0x80f0
	s_lshl_b32 s31, s28, 14
	s_add_u32 s31, s31, 0x3ff0
	s_mul_i32 s3, s30, 0x1800
	s_add_u32 s6, s4, s3
	s_addc_u32 s7, s5, 0
	s_add_u32 s6, s6, 0x2f914000
	s_addc_u32 s7, s7, 0
	s_mul_i32 s3, s30, 0x1000
	s_add_u32 s8, s4, s3
	s_addc_u32 s9, s5, 0
	s_add_u32 s8, s8, 0xbe4c000
	s_addc_u32 s9, s9, 0
	s_mul_i32 s3, s31, 0x1800
	s_add_u32 s14, s4, s3
	s_addc_u32 s15, s5, 0
	s_add_u32 s14, s14, 0x2f914000
	s_addc_u32 s15, s15, 0
	s_mul_i32 s3, s31, 0x1000
	s_add_u32 s16, s4, s3
	s_addc_u32 s17, s5, 0
	s_add_u32 s16, s16, 0xbe4c000
	s_addc_u32 s17, s17, 0
	s_mov_b32 s29, 0
	v_add_u32_e32 v13, 0, v12
	global_load_dwordx4 v[16:19], v10, s[6:7]
	global_load_dwordx2 v[20:21], v10, s[6:7] offset:16
	global_load_dwordx4 v[24:27], v11, s[8:9]
	s_add_u32 s29, s29, 1
	s_cmp_eq_u32 s29, 16
	s_cbranch_scc1 .Lscan_stsw_p0_f1
	s_sub_u32 s6, s6, 0x18000
	s_subb_u32 s7, s7, 0
	s_sub_u32 s8, s8, 0x10000
	s_subb_u32 s9, s9, 0
	s_branch .Lscan_stdone_p0_f1

.Lscan_stdone_p0_f1:
	s_waitcnt vmcnt(0)
	v_cvt_f32_f16_e32 v32, v16
	v_cvt_f32_f16_sdwa v33, v16 dst_sel:DWORD dst_unused:UNUSED_PAD src0_sel:WORD_1
	v_cvt_f32_f16_e32 v34, v17
	v_cvt_f32_f16_sdwa v35, v17 dst_sel:DWORD dst_unused:UNUSED_PAD src0_sel:WORD_1
	v_cvt_f32_f16_e32 v36, v18
	v_cvt_f32_f16_sdwa v37, v18 dst_sel:DWORD dst_unused:UNUSED_PAD src0_sel:WORD_1
	v_cvt_f32_f16_e32 v38, v19
	v_cvt_f32_f16_sdwa v39, v19 dst_sel:DWORD dst_unused:UNUSED_PAD src0_sel:WORD_1
	v_cvt_f32_f16_e32 v40, v20
	v_cvt_f32_f16_sdwa v41, v20 dst_sel:DWORD dst_unused:UNUSED_PAD src0_sel:WORD_1
	v_cvt_f32_f16_e32 v42, v21
	v_cvt_f32_f16_sdwa v43, v21 dst_sel:DWORD dst_unused:UNUSED_PAD src0_sel:WORD_1
	v_cvt_f32_f16_e32 v44, v24
	v_cvt_f32_f16_sdwa v45, v24 dst_sel:DWORD dst_unused:UNUSED_PAD src0_sel:WORD_1
	v_cvt_f32_f16_e32 v46, v25
	v_cvt_f32_f16_sdwa v47, v25 dst_sel:DWORD dst_unused:UNUSED_PAD src0_sel:WORD_1
	v_cvt_f32_f16_e32 v48, v26
	v_cvt_f32_f16_sdwa v49, v26 dst_sel:DWORD dst_unused:UNUSED_PAD src0_sel:WORD_1
	v_cvt_f32_f16_e32 v50, v27
	v_cvt_f32_f16_sdwa v51, v27 dst_sel:DWORD dst_unused:UNUSED_PAD src0_sel:WORD_1
	ds_write_b128 v13, v[32:35]
	ds_write_b128 v13, v[36:39] offset:4096
	ds_write_b128 v13, v[40:43] offset:8192
	ds_write_b128 v13, v[44:47] offset:12288
	ds_write_b128 v13, v[48:51] offset:16384
	v_add_u32_e32 v13, 20480, v12
	global_load_dwordx4 v[16:19], v10, s[6:7]
	global_load_dwordx2 v[20:21], v10, s[6:7] offset:16
	global_load_dwordx4 v[24:27], v11, s[8:9]
	s_add_u32 s29, s29, 1
	s_cmp_eq_u32 s29, 16
	s_cbranch_scc1 .Lscan_stsw_p1_f1
	s_sub_u32 s6, s6, 0x18000
	s_subb_u32 s7, s7, 0
	s_sub_u32 s8, s8, 0x10000
	s_subb_u32 s9, s9, 0
	s_branch .Lscan_stdone_p1_f1

.Lscan_stdone_p1_f1:
	s_waitcnt vmcnt(0)
	v_cvt_f32_f16_e32 v32, v16
	v_cvt_f32_f16_sdwa v33, v16 dst_sel:DWORD dst_unused:UNUSED_PAD src0_sel:WORD_1
	v_cvt_f32_f16_e32 v34, v17
	v_cvt_f32_f16_sdwa v35, v17 dst_sel:DWORD dst_unused:UNUSED_PAD src0_sel:WORD_1
	v_cvt_f32_f16_e32 v36, v18
	v_cvt_f32_f16_sdwa v37, v18 dst_sel:DWORD dst_unused:UNUSED_PAD src0_sel:WORD_1
	v_cvt_f32_f16_e32 v38, v19
	v_cvt_f32_f16_sdwa v39, v19 dst_sel:DWORD dst_unused:UNUSED_PAD src0_sel:WORD_1
	v_cvt_f32_f16_e32 v40, v20
	v_cvt_f32_f16_sdwa v41, v20 dst_sel:DWORD dst_unused:UNUSED_PAD src0_sel:WORD_1
	v_cvt_f32_f16_e32 v42, v21
	v_cvt_f32_f16_sdwa v43, v21 dst_sel:DWORD dst_unused:UNUSED_PAD src0_sel:WORD_1
	v_cvt_f32_f16_e32 v44, v24
	v_cvt_f32_f16_sdwa v45, v24 dst_sel:DWORD dst_unused:UNUSED_PAD src0_sel:WORD_1
	v_cvt_f32_f16_e32 v46, v25
	v_cvt_f32_f16_sdwa v47, v25 dst_sel:DWORD dst_unused:UNUSED_PAD src0_sel:WORD_1
	v_cvt_f32_f16_e32 v48, v26
	v_cvt_f32_f16_sdwa v49, v26 dst_sel:DWORD dst_unused:UNUSED_PAD src0_sel:WORD_1
	v_cvt_f32_f16_e32 v50, v27
	v_cvt_f32_f16_sdwa v51, v27 dst_sel:DWORD dst_unused:UNUSED_PAD src0_sel:WORD_1
	ds_write_b128 v13, v[32:35]
	ds_write_b128 v13, v[36:39] offset:4096
	ds_write_b128 v13, v[40:43] offset:8192
	ds_write_b128 v13, v[44:47] offset:12288
	ds_write_b128 v13, v[48:51] offset:16384
	global_load_dwordx4 v[16:19], v10, s[6:7]
	global_load_dwordx2 v[20:21], v10, s[6:7] offset:16
	global_load_dwordx4 v[24:27], v11, s[8:9]
	s_add_u32 s29, s29, 1
	s_cmp_eq_u32 s29, 16
	s_cbranch_scc1 .Lscan_stsw_p2_f1
	s_sub_u32 s6, s6, 0x18000
	s_subb_u32 s7, s7, 0
	s_sub_u32 s8, s8, 0x10000
	s_subb_u32 s9, s9, 0
	s_branch .Lscan_stdone_p2_f1

; template <int VAR>
; __device__ __forceinline__ void ph_rw_scan(const Params& P) {
;     ...
;   for (int wu = blockIdx.x * 4 + wave; wave < 4 && wu < NWU; wu += gridDim.x * 4) {
;     const int rg = wu % 16, hh = (wu / 16) % RW_H, b = (wu / (16 * RW_H)) % BATCH, dir = wu / (16 * RW_H * BATCH);
.Lscan_next:
	v_readfirstlane_b32 s1, v0
	s_lshr_b32 s1, s1, 6
	s_lshl_b32 s30, s84, 2
	s_add_u32 s0, s0, s30
	s_cmp_lt_u32 s0, 0x400
	s_cbranch_scc1 .Lscan_unit
